# mLSTM M3 item front/tail load de-serialisation: n_prev load beside gate loads, second conv tile's 19 loads behind the first tile's, output-gate loads before the last MFMA stage
# baseline (speedup 1.0000x reference)
; __device__ __forceinline__ unsigned cvt_pk_bf16(float lo, float hi) { const f32x2_t v = {lo, hi}; const bf16x2_t b = __builtin_convertvector(v, bf16x2_t); return __builtin_bit_cast(unsigned, b); }
; __device__ __forceinline__ float bflo(unsigned u) { return __uint_as_float(u << 16); }
; __device__ __forceinline__ float bfhi(unsigned u) { return __uint_as_float(u & 0xffff0000u); }
; __device__ __forceinline__ void m3_item(LAS char* lds, bf16_t* proj, const float* gif, const bf16_t* Cst, const float* nst, const float* mprev, const float* convw, int bhl, int c) {
;     ...
;     const float rdn = 1.0f / fmaxf(fabsf(den), __expf(-mt));
;     bf16_t* op = proj + SEC(C_MO) + (size_t)(t0 + jj) * PP + h * 256 + 4 * g;
;     u32x2 sgv[16];
; #pragma unroll
;     for (int nb = 0; nb < 16; ++nb) sgv[nb] = *(const u32x2*)(op + 16 * nb);
; #pragma unroll
;     for (int nb = 0; nb < 16; ++nb) { const u32x2 sg = sgv[nb];
;         u32x2 w; w.x = cvt_pk_bf16(acc[nb][0] * rdn * bflo(sg.x), acc[nb][1] * rdn * bfhi(sg.x)); w.y = cvt_pk_bf16(acc[nb][2] * rdn * bflo(sg.y), acc[nb][3] * rdn * bfhi(sg.y));
;         *(u32x2*)(op + 16 * nb) = w; }
.LBB0_163:
	v_pk_add_f32 v[2:3], v[2:3], v[106:107]
	v_readlane_b32 s0, v252, 18
	v_fmac_f32_e32 v3, v2, v0
	v_mul_f32_e32 v0, 0xbfb8aa3b, v144
	v_exp_f32_e32 v0, v0
	v_add_u32_e32 v2, s74, v105
	v_readlane_b32 s1, v252, 19
	s_add_i32 s72, s72, s94
	v_max_f32_e64 v100, |v3|, v0
	v_ashrrev_i32_e32 v3, 31, v2
	v_lshlrev_b64 v[2:3], 11, v[2:3]
	v_lshl_add_u64 v[2:3], s[0:1], 0, v[2:3]
	v_lshl_add_u64 v[2:3], v[2:3], 0, s[84:85]
	v_lshlrev_b32_e32 v0, 1, v142
	v_lshl_add_u64 v[2:3], v[2:3], 0, v[0:1]
	s_waitcnt vmcnt(0)
	v_mov_b64_e32 v[30:31], v[206:207]
	v_mov_b64_e32 v[32:33], v[208:209]
	v_mov_b64_e32 v[34:35], v[210:211]
	v_mov_b64_e32 v[28:29], v[212:213]
	v_mov_b64_e32 v[24:25], v[214:215]
	v_mov_b64_e32 v[26:27], v[216:217]
	v_mov_b64_e32 v[22:23], v[218:219]
	v_mov_b64_e32 v[20:21], v[220:221]
	v_mov_b64_e32 v[18:19], v[222:223]
	v_mov_b64_e32 v[16:17], v[224:225]
	v_mov_b64_e32 v[14:15], v[226:227]
	v_mov_b64_e32 v[12:13], v[228:229]
	v_mov_b64_e32 v[10:11], v[238:239]
	v_mov_b64_e32 v[8:9], v[240:241]
	v_mov_b64_e32 v[6:7], v[244:245]
	v_mov_b64_e32 v[4:5], v[246:247]
	v_div_scale_f32 v0, s[0:1], v100, v100, 1.0
	v_rcp_f32_e32 v101, v0
	s_cmpk_gt_i32 s72, 0x1ff
	v_fma_f32 v102, -v0, v101, 1.0
	v_fmac_f32_e32 v101, v102, v101
	v_div_scale_f32 v102, vcc, 1.0, v100, 1.0
	v_mul_f32_e32 v103, v102, v101
	v_fma_f32 v104, -v0, v103, v102
	v_fmac_f32_e32 v103, v104, v101
	v_fma_f32 v0, -v0, v103, v102
	v_div_fmas_f32 v0, v0, v101, v103
	v_div_fixup_f32 v0, v0, v100, 1.0
	v_pk_mul_f32 v[96:97], v[0:1], v[96:97] op_sel_hi:[0,1]
	s_waitcnt vmcnt(15)
	v_lshlrev_b32_e32 v100, 16, v30
	v_and_b32_e32 v101, 0xffff0000, v30
	v_pk_mul_f32 v[96:97], v[96:97], v[100:101]
	s_nop 0
	v_cvt_pk_bf16_f32 v30, v96, v97
	v_pk_mul_f32 v[96:97], v[0:1], v[98:99] op_sel_hi:[0,1]
	v_lshlrev_b32_e32 v98, 16, v31
	v_and_b32_e32 v99, 0xffff0000, v31
	v_pk_mul_f32 v[96:97], v[96:97], v[98:99]
	s_nop 0
	v_cvt_pk_bf16_f32 v31, v96, v97
	global_store_dwordx2 v[2:3], v[30:31], off
	v_pk_mul_f32 v[30:31], v[0:1], v[92:93] op_sel_hi:[0,1]
	s_waitcnt vmcnt(15)
	v_lshlrev_b32_e32 v92, 16, v32
	v_and_b32_e32 v93, 0xffff0000, v32
	v_pk_mul_f32 v[30:31], v[30:31], v[92:93]
	v_pk_mul_f32 v[92:93], v[0:1], v[94:95] op_sel_hi:[0,1]
	v_lshlrev_b32_e32 v32, 16, v33
	v_and_b32_e32 v33, 0xffff0000, v33
	v_pk_mul_f32 v[32:33], v[92:93], v[32:33]
	v_cvt_pk_bf16_f32 v30, v30, v31
	v_cvt_pk_bf16_f32 v31, v32, v33
	global_store_dwordx2 v[2:3], v[30:31], off offset:32
	v_pk_mul_f32 v[30:31], v[0:1], v[88:89] op_sel_hi:[0,1]
	s_waitcnt vmcnt(15)
	v_lshlrev_b32_e32 v32, 16, v34
	v_and_b32_e32 v33, 0xffff0000, v34
	v_pk_mul_f32 v[30:31], v[30:31], v[32:33]
	v_pk_mul_f32 v[32:33], v[0:1], v[90:91] op_sel_hi:[0,1]
	v_lshlrev_b32_e32 v34, 16, v35
	v_and_b32_e32 v35, 0xffff0000, v35
	v_pk_mul_f32 v[32:33], v[32:33], v[34:35]
	v_cvt_pk_bf16_f32 v30, v30, v31
	v_cvt_pk_bf16_f32 v31, v32, v33
	global_store_dwordx2 v[2:3], v[30:31], off offset:64
	v_pk_mul_f32 v[30:31], v[0:1], v[84:85] op_sel_hi:[0,1]
	s_waitcnt vmcnt(15)
	v_lshlrev_b32_e32 v32, 16, v28
	v_and_b32_e32 v33, 0xffff0000, v28
	v_pk_mul_f32 v[30:31], v[30:31], v[32:33]
	v_lshlrev_b32_e32 v32, 16, v29
	v_cvt_pk_bf16_f32 v28, v30, v31
	v_pk_mul_f32 v[30:31], v[0:1], v[86:87] op_sel_hi:[0,1]
	v_and_b32_e32 v33, 0xffff0000, v29
	v_pk_mul_f32 v[30:31], v[30:31], v[32:33]
	s_nop 0
	v_cvt_pk_bf16_f32 v29, v30, v31
	global_store_dwordx2 v[2:3], v[28:29], off offset:96
	v_pk_mul_f32 v[28:29], v[0:1], v[80:81] op_sel_hi:[0,1]
	s_waitcnt vmcnt(15)
	v_lshlrev_b32_e32 v30, 16, v24
	v_and_b32_e32 v31, 0xffff0000, v24
	v_pk_mul_f32 v[28:29], v[28:29], v[30:31]
	v_lshlrev_b32_e32 v30, 16, v25
	v_cvt_pk_bf16_f32 v24, v28, v29
	v_pk_mul_f32 v[28:29], v[0:1], v[82:83] op_sel_hi:[0,1]
	v_and_b32_e32 v31, 0xffff0000, v25
	v_pk_mul_f32 v[28:29], v[28:29], v[30:31]
	s_nop 0
	v_cvt_pk_bf16_f32 v25, v28, v29
	global_store_dwordx2 v[2:3], v[24:25], off offset:128
	v_pk_mul_f32 v[24:25], v[0:1], v[76:77] op_sel_hi:[0,1]
	s_waitcnt vmcnt(15)
	v_lshlrev_b32_e32 v28, 16, v26
	v_and_b32_e32 v29, 0xffff0000, v26
	v_pk_mul_f32 v[24:25], v[24:25], v[28:29]
	v_pk_mul_f32 v[28:29], v[0:1], v[78:79] op_sel_hi:[0,1]
	v_lshlrev_b32_e32 v26, 16, v27
	v_and_b32_e32 v27, 0xffff0000, v27
	v_pk_mul_f32 v[26:27], v[28:29], v[26:27]
	v_cvt_pk_bf16_f32 v24, v24, v25
	v_cvt_pk_bf16_f32 v25, v26, v27
	global_store_dwordx2 v[2:3], v[24:25], off offset:160
	v_pk_mul_f32 v[24:25], v[0:1], v[72:73] op_sel_hi:[0,1]
	s_waitcnt vmcnt(15)
	v_lshlrev_b32_e32 v26, 16, v22
	v_and_b32_e32 v27, 0xffff0000, v22
	v_pk_mul_f32 v[24:25], v[24:25], v[26:27]
	v_lshlrev_b32_e32 v26, 16, v23
	v_cvt_pk_bf16_f32 v22, v24, v25
	v_pk_mul_f32 v[24:25], v[0:1], v[74:75] op_sel_hi:[0,1]
	v_and_b32_e32 v27, 0xffff0000, v23
	v_pk_mul_f32 v[24:25], v[24:25], v[26:27]
	s_nop 0
	v_cvt_pk_bf16_f32 v23, v24, v25
	global_store_dwordx2 v[2:3], v[22:23], off offset:192
	v_pk_mul_f32 v[22:23], v[0:1], v[68:69] op_sel_hi:[0,1]
	s_waitcnt vmcnt(15)
	v_lshlrev_b32_e32 v24, 16, v20
	v_and_b32_e32 v25, 0xffff0000, v20
	v_pk_mul_f32 v[22:23], v[22:23], v[24:25]
	v_lshlrev_b32_e32 v24, 16, v21
	v_cvt_pk_bf16_f32 v20, v22, v23
	v_pk_mul_f32 v[22:23], v[0:1], v[70:71] op_sel_hi:[0,1]
	v_and_b32_e32 v25, 0xffff0000, v21
	v_pk_mul_f32 v[22:23], v[22:23], v[24:25]
	s_nop 0
	v_cvt_pk_bf16_f32 v21, v22, v23
	global_store_dwordx2 v[2:3], v[20:21], off offset:224
	v_pk_mul_f32 v[20:21], v[0:1], v[64:65] op_sel_hi:[0,1]
	s_waitcnt vmcnt(15)
; __device__ __forceinline__ unsigned cvt_pk_bf16(float lo, float hi) { const f32x2_t v = {lo, hi}; const bf16x2_t b = __builtin_convertvector(v, bf16x2_t); return __builtin_bit_cast(unsigned, b); }
; __device__ __forceinline__ float bflo(unsigned u) { return __uint_as_float(u << 16); }
; __device__ __forceinline__ float bfhi(unsigned u) { return __uint_as_float(u & 0xffff0000u); }
; #define LAS __attribute__((address_space(3)))
; __device__ __forceinline__ void load_gates(LAS float* vec, const float* gif, int t0, int h, int tid) {
;     LAS float* li = vec; LAS float* bc = vec + 128; LAS float* tot = vec + 256;
;     const int lane = tid & 63;
;     float v = 0.f;
;     if (tid < 128) { li[tid] = gif[(size_t)(t0 + tid) * 8 + h]; v = gif[(size_t)(t0 + tid) * 8 + 4 + h];
; #pragma unroll
;         for (int o = 1; o < 64; o <<= 1) { const float uu = __shfl_up(v, o); if (lane >= o) v += uu; }
;         if (tid == 63) tot[0] = v; }
; __device__ __forceinline__ void m3_item(LAS char* lds, bf16_t* proj, const float* gif, const bf16_t* Cst, const float* nst, const float* mprev, const float* convw, int bhl, int c) {
;     ...
;     for (int nb = 0; nb < 16; ++nb) { const u32x2 sg = sgv[nb];
;         u32x2 w; w.x = cvt_pk_bf16(acc[nb][0] * rdn * bflo(sg.x), acc[nb][1] * rdn * bfhi(sg.x)); w.y = cvt_pk_bf16(acc[nb][2] * rdn * bflo(sg.y), acc[nb][3] * rdn * bfhi(sg.y));
;         *(u32x2*)(op + 16 * nb) = w; }
;     __syncthreads();
	v_lshlrev_b32_e32 v22, 16, v18
	v_and_b32_e32 v23, 0xffff0000, v18
	v_pk_mul_f32 v[20:21], v[20:21], v[22:23]
	v_lshlrev_b32_e32 v22, 16, v19
	v_cvt_pk_bf16_f32 v18, v20, v21
	v_pk_mul_f32 v[20:21], v[0:1], v[66:67] op_sel_hi:[0,1]
	v_and_b32_e32 v23, 0xffff0000, v19
	v_pk_mul_f32 v[20:21], v[20:21], v[22:23]
	s_nop 0
	v_cvt_pk_bf16_f32 v19, v20, v21
	global_store_dwordx2 v[2:3], v[18:19], off offset:256
	v_pk_mul_f32 v[18:19], v[0:1], v[60:61] op_sel_hi:[0,1]
	s_waitcnt vmcnt(15)
	v_lshlrev_b32_e32 v20, 16, v16
	v_and_b32_e32 v21, 0xffff0000, v16
	v_pk_mul_f32 v[18:19], v[18:19], v[20:21]
	v_lshlrev_b32_e32 v20, 16, v17
	v_cvt_pk_bf16_f32 v16, v18, v19
	v_pk_mul_f32 v[18:19], v[0:1], v[62:63] op_sel_hi:[0,1]
	v_and_b32_e32 v21, 0xffff0000, v17
	v_pk_mul_f32 v[18:19], v[18:19], v[20:21]
	s_nop 0
	v_cvt_pk_bf16_f32 v17, v18, v19
	global_store_dwordx2 v[2:3], v[16:17], off offset:288
	v_pk_mul_f32 v[16:17], v[0:1], v[56:57] op_sel_hi:[0,1]
	s_waitcnt vmcnt(15)
	v_lshlrev_b32_e32 v18, 16, v14
	v_and_b32_e32 v19, 0xffff0000, v14
	v_pk_mul_f32 v[16:17], v[16:17], v[18:19]
	v_lshlrev_b32_e32 v18, 16, v15
	v_cvt_pk_bf16_f32 v14, v16, v17
	v_pk_mul_f32 v[16:17], v[0:1], v[58:59] op_sel_hi:[0,1]
	v_and_b32_e32 v19, 0xffff0000, v15
	v_pk_mul_f32 v[16:17], v[16:17], v[18:19]
	s_nop 0
	v_cvt_pk_bf16_f32 v15, v16, v17
	global_store_dwordx2 v[2:3], v[14:15], off offset:320
	v_pk_mul_f32 v[14:15], v[0:1], v[52:53] op_sel_hi:[0,1]
	s_waitcnt vmcnt(15)
	v_lshlrev_b32_e32 v16, 16, v12
	v_and_b32_e32 v17, 0xffff0000, v12
	v_pk_mul_f32 v[14:15], v[14:15], v[16:17]
	v_lshlrev_b32_e32 v16, 16, v13
	v_cvt_pk_bf16_f32 v12, v14, v15
	v_pk_mul_f32 v[14:15], v[0:1], v[54:55] op_sel_hi:[0,1]
	v_and_b32_e32 v17, 0xffff0000, v13
	v_pk_mul_f32 v[14:15], v[14:15], v[16:17]
	s_nop 0
	v_cvt_pk_bf16_f32 v13, v14, v15
	global_store_dwordx2 v[2:3], v[12:13], off offset:352
	v_pk_mul_f32 v[12:13], v[0:1], v[48:49] op_sel_hi:[0,1]
	s_waitcnt vmcnt(15)
	v_lshlrev_b32_e32 v14, 16, v10
	v_and_b32_e32 v15, 0xffff0000, v10
	v_pk_mul_f32 v[12:13], v[12:13], v[14:15]
	v_lshlrev_b32_e32 v14, 16, v11
	v_cvt_pk_bf16_f32 v10, v12, v13
	v_pk_mul_f32 v[12:13], v[0:1], v[50:51] op_sel_hi:[0,1]
	v_and_b32_e32 v15, 0xffff0000, v11
	v_pk_mul_f32 v[12:13], v[12:13], v[14:15]
	s_nop 0
	v_cvt_pk_bf16_f32 v11, v12, v13
	global_store_dwordx2 v[2:3], v[10:11], off offset:384
	v_pk_mul_f32 v[10:11], v[0:1], v[44:45] op_sel_hi:[0,1]
	s_waitcnt vmcnt(15)
	v_lshlrev_b32_e32 v12, 16, v8
	v_and_b32_e32 v13, 0xffff0000, v8
	v_pk_mul_f32 v[10:11], v[10:11], v[12:13]
	v_lshlrev_b32_e32 v12, 16, v9
	v_cvt_pk_bf16_f32 v8, v10, v11
	v_pk_mul_f32 v[10:11], v[0:1], v[46:47] op_sel_hi:[0,1]
	v_and_b32_e32 v13, 0xffff0000, v9
	v_pk_mul_f32 v[10:11], v[10:11], v[12:13]
	s_nop 0
	v_cvt_pk_bf16_f32 v9, v10, v11
	global_store_dwordx2 v[2:3], v[8:9], off offset:416
	v_pk_mul_f32 v[8:9], v[0:1], v[40:41] op_sel_hi:[0,1]
	s_waitcnt vmcnt(15)
	v_lshlrev_b32_e32 v10, 16, v6
	v_and_b32_e32 v11, 0xffff0000, v6
	v_pk_mul_f32 v[8:9], v[8:9], v[10:11]
	v_lshlrev_b32_e32 v10, 16, v7
	v_cvt_pk_bf16_f32 v6, v8, v9
	v_pk_mul_f32 v[8:9], v[0:1], v[42:43] op_sel_hi:[0,1]
	v_and_b32_e32 v11, 0xffff0000, v7
	v_pk_mul_f32 v[8:9], v[8:9], v[10:11]
	s_nop 0
	v_cvt_pk_bf16_f32 v7, v8, v9
	global_store_dwordx2 v[2:3], v[6:7], off offset:448
	v_pk_mul_f32 v[6:7], v[0:1], v[36:37] op_sel_hi:[0,1]
	s_waitcnt vmcnt(15)
	v_lshlrev_b32_e32 v8, 16, v4
	v_and_b32_e32 v9, 0xffff0000, v4
	v_pk_mul_f32 v[6:7], v[6:7], v[8:9]
	v_lshlrev_b32_e32 v8, 16, v5
	v_cvt_pk_bf16_f32 v4, v6, v7
	v_pk_mul_f32 v[6:7], v[0:1], v[38:39] op_sel_hi:[0,1]
	v_and_b32_e32 v9, 0xffff0000, v5
	v_pk_mul_f32 v[6:7], v[6:7], v[8:9]
	s_nop 0
	v_cvt_pk_bf16_f32 v5, v6, v7
	global_store_dwordx2 v[2:3], v[4:5], off offset:480
	s_barrier
	s_cbranch_scc1 .LBB0_206
.LBB0_164:
	s_ashr_i32 s0, s72, 5
	s_and_b32 s11, s0, 3
	s_lshl_b32 s0, s0, 10
	s_lshl_b32 s1, s72, 7
	v_mov_b32_e32 v104, v194
	s_and_b32 s0, s0, 0xfffff000
	s_and_b32 s12, s1, 0xf80
	s_or_b32 s74, s0, s12
	v_and_b32_e32 v126, 63, v104
	v_readfirstlane_b32 s10, v104
	v_cmp_gt_i32_e32 vcc, s47, v104
	v_mov_b32_e32 v2, 0
	v_lshl_add_u32 v0, v104, 2, 0
	s_mov_b32 s98, s72
	s_ashr_i32 s99, s72, 31
	s_lshl_b64 s[98:99], s[98:99], 10
	v_readlane_b32 s100, v252, 8
	v_readlane_b32 s101, v252, 9
	s_add_u32 s98, s100, s98
	s_addc_u32 s99, s101, s99
	global_load_dword v243, v0, s[98:99]
	s_and_saveexec_b64 s[6:7], vcc
	s_cbranch_execz .LBB0_168
	v_add_u32_e32 v2, s74, v104
	v_ashrrev_i32_e32 v3, 31, v2
	v_readlane_b32 s0, v252, 41
	v_lshlrev_b64 v[2:3], 5, v[2:3]
	v_readlane_b32 s1, v252, 42
	s_lshl_b32 s84, s11, 2
	v_add_u32_e32 v5, 0x22000, v0
	v_lshl_add_u64 v[2:3], s[0:1], 0, v[2:3]
	v_lshl_add_u64 v[2:3], v[2:3], 0, s[84:85]
	global_load_dword v4, v[2:3], off
	v_cmp_eq_u32_e64 s[4:5], 63, v104
	global_load_dword v2, v[2:3], off offset:16
	v_and_b32_e32 v3, 64, v235
	s_waitcnt vmcnt(0)
	ds_write_b32 v5, v4
	v_add_u32_e32 v4, -1, v235
	v_cmp_lt_i32_e64 s[0:1], v4, v3
	s_nop 1
	v_cndmask_b32_e64 v4, v4, v235, s[0:1]
	v_lshlrev_b32_e32 v4, 2, v4
	ds_bpermute_b32 v4, v4, v2
	v_cmp_eq_u32_e64 s[0:1], 0, v126
	s_waitcnt lgkmcnt(0)
	v_add_f32_e32 v4, v2, v4
	v_cndmask_b32_e64 v2, v4, v2, s[0:1]
	v_add_u32_e32 v4, -2, v235
	v_cmp_lt_i32_e64 s[0:1], v4, v3
	s_nop 1
	v_cndmask_b32_e64 v4, v4, v235, s[0:1]
	v_lshlrev_b32_e32 v4, 2, v4
	ds_bpermute_b32 v4, v4, v2
	v_cmp_gt_u32_e64 s[0:1], 2, v126
	s_waitcnt lgkmcnt(0)
	v_add_f32_e32 v4, v2, v4
	v_cndmask_b32_e64 v2, v4, v2, s[0:1]
	v_add_u32_e32 v4, -4, v235
	v_cmp_lt_i32_e64 s[0:1], v4, v3
	s_nop 1
	v_cndmask_b32_e64 v4, v4, v235, s[0:1]
	v_lshlrev_b32_e32 v4, 2, v4
	ds_bpermute_b32 v4, v4, v2
	v_cmp_gt_u32_e64 s[0:1], 4, v126
	s_waitcnt lgkmcnt(0)
	v_add_f32_e32 v4, v2, v4
	v_cndmask_b32_e64 v2, v4, v2, s[0:1]
	v_add_u32_e32 v4, -8, v235
	v_cmp_lt_i32_e64 s[0:1], v4, v3
	s_nop 1
	v_cndmask_b32_e64 v4, v4, v235, s[0:1]
	v_lshlrev_b32_e32 v4, 2, v4
	ds_bpermute_b32 v4, v4, v2
	v_cmp_gt_u32_e64 s[0:1], 8, v126
	s_waitcnt lgkmcnt(0)
	v_add_f32_e32 v4, v2, v4
	v_cndmask_b32_e64 v2, v4, v2, s[0:1]
	v_add_u32_e32 v4, -16, v235
	v_cmp_lt_i32_e64 s[0:1], v4, v3
	s_nop 1
	v_cndmask_b32_e64 v4, v4, v235, s[0:1]
	v_lshlrev_b32_e32 v4, 2, v4
	ds_bpermute_b32 v4, v4, v2
	v_cmp_gt_u32_e64 s[0:1], 16, v126
	s_waitcnt lgkmcnt(0)
	v_add_f32_e32 v4, v2, v4
	v_cndmask_b32_e64 v2, v4, v2, s[0:1]
	v_subrev_u32_e32 v4, 32, v235
	v_cmp_lt_i32_e64 s[0:1], v4, v3
	s_nop 1
	v_cndmask_b32_e64 v3, v4, v235, s[0:1]
	v_lshlrev_b32_e32 v3, 2, v3
	ds_bpermute_b32 v3, v3, v2
	v_cmp_gt_u32_e64 s[0:1], 32, v126
	s_waitcnt lgkmcnt(0)
	v_add_f32_e32 v3, v2, v3
	s_and_saveexec_b64 s[8:9], s[4:5]
	s_cbranch_execz .LBB0_167
	v_readlane_b32 s4, v254, 35
	s_nop 1
	v_mov_b32_e32 v4, s4
	ds_write_b32 v4, v3

; __device__ __forceinline__ void m3_item(LAS char* lds, bf16_t* proj, const float* gif, const bf16_t* Cst, const float* nst, const float* mprev, const float* convw, int bhl, int c) {
;     ...
;     if (tid < 256) npv[tid] = nst[(size_t)item * 256 + tid];
.LBB0_172:
	s_or_b64 exec, exec, s[0:1]
	s_movk_i32 s0, 0x100
	v_cmp_gt_i32_e32 vcc, s0, v104
	s_and_saveexec_b64 s[0:1], vcc
	s_cbranch_execz .LBB0_174
	s_ashr_i32 s73, s72, 31
	s_lshl_b64 s[4:5], s[72:73], 10
	v_readlane_b32 s6, v252, 8
	v_readlane_b32 s7, v252, 9
	s_add_u32 s4, s6, s4
	s_addc_u32 s5, s7, s5
	v_ashrrev_i32_e32 v105, 31, v104
	v_lshl_add_u64 v[2:3], v[104:105], 2, s[4:5]
	v_add_u32_e32 v0, 0x22440, v0
	s_waitcnt vmcnt(0)
	ds_write_b32 v0, v243

; #define LAS __attribute__((address_space(3)))
; __device__ __forceinline__ void load_conv(LAS char* dst, const bf16_t* src, int pos0, const float* cw  , const LAS float* rowscale, float cscale, int tid) {
;     const int cg = tid & 31, rs = tid >> 5, r0 = rs * 8;
;     u32x4 rw[11];
; #pragma unroll
;     for (int j = 0; j < 11; ++j) { const int rr = r0 - 3 + j;
;         if (j >= 3 || pos0 + rr >= 0) rw[j] = *(const u32x4*)(src + (ptrdiff_t)rr * PP + cg * 8); else rw[j] = (u32x4){0u, 0u, 0u, 0u}; }
;     float w[4][8];
; #pragma unroll
;     for (int j = 0; j < 4; ++j) { const f32x4 a = *(const f32x4*)(cw + j * 2048 + cg * 8), b = *(const f32x4*)(cw + j * 2048 + cg * 8 + 4);
;         w[j][0] = a.x; w[j][1] = a.y; w[j][2] = a.z; w[j][3] = a.w; w[j][4] = b.x; w[j][5] = b.y; w[j][6] = b.z; w[j][7] = b.w; }
; __device__ __forceinline__ void m3_item(LAS char* lds, bf16_t* proj, const float* gif, const bf16_t* Cst, const float* nst, const float* mprev, const float* convw, int bhl, int c) {
;     ...
;     load_conv(X, proj + SEC(C_MQ) + (size_t)t0 * PP + h * 256, c * 128, convw + h * 256, nullptr, 0.0625f, tid);
;     load_conv(Y, proj + SEC(C_MK) + (size_t)t0 * PP + h * 256, c * 128, convw + 1024 + h * 256, nullptr, 1.0f, tid);
.LBB0_180:
	s_or_b64 exec, exec, s[0:1]
	v_ashrrev_i32_e32 v111, 31, v110
	v_lshlrev_b64 v[86:87], 11, v[110:111]
	v_lshl_add_u64 v[8:9], v[4:5], 0, v[86:87]
	global_load_dwordx4 v[76:79], v[8:9], off
	v_or_b32_e32 v8, 1, v110
	v_ashrrev_i32_e32 v9, 31, v8
	v_lshlrev_b64 v[88:89], 11, v[8:9]
	v_lshl_add_u64 v[8:9], v[4:5], 0, v[88:89]
	global_load_dwordx4 v[60:63], v[8:9], off
	v_or_b32_e32 v8, 2, v110
	v_ashrrev_i32_e32 v9, 31, v8
	v_lshlrev_b64 v[90:91], 11, v[8:9]
	v_lshl_add_u64 v[8:9], v[4:5], 0, v[90:91]
	global_load_dwordx4 v[56:59], v[8:9], off
	v_or_b32_e32 v8, 3, v110
	v_ashrrev_i32_e32 v9, 31, v8
	v_lshlrev_b64 v[92:93], 11, v[8:9]
	v_lshl_add_u64 v[8:9], v[4:5], 0, v[92:93]
	global_load_dwordx4 v[52:55], v[8:9], off
	v_or_b32_e32 v8, 4, v110
	v_ashrrev_i32_e32 v9, 31, v8
	v_lshlrev_b64 v[94:95], 11, v[8:9]
	v_lshl_add_u64 v[8:9], v[4:5], 0, v[94:95]
	global_load_dwordx4 v[48:51], v[8:9], off
	v_or_b32_e32 v8, 5, v110
	v_ashrrev_i32_e32 v9, 31, v8
	v_lshlrev_b64 v[96:97], 11, v[8:9]
	v_lshl_add_u64 v[8:9], v[4:5], 0, v[96:97]
	global_load_dwordx4 v[44:47], v[8:9], off
	v_or_b32_e32 v8, 6, v110
	v_or_b32_e32 v106, 7, v6
	s_lshl_b32 s11, s12, 2
	v_readlane_b32 s0, v255, 18
	v_ashrrev_i32_e32 v9, 31, v8
	v_ashrrev_i32_e32 v107, 31, v106
	v_lshlrev_b32_e32 v3, 3, v3
	s_add_u32 s0, s0, s11
	v_readlane_b32 s1, v255, 20
	v_lshlrev_b64 v[98:99], 11, v[8:9]
	v_lshlrev_b64 v[100:101], 11, v[106:107]
	s_addc_u32 s1, s1, 0
	v_lshl_add_u64 v[8:9], v[4:5], 0, v[98:99]
	v_lshl_add_u64 v[4:5], v[4:5], 0, v[100:101]
	v_lshlrev_b32_e32 v102, 2, v3
	v_mov_b32_e32 v103, v1
	global_load_dwordx4 v[24:27], v[8:9], off
	v_lshl_add_u64 v[20:21], s[0:1], 0, v[102:103]
	global_load_dwordx4 v[4:7], v[4:5], off
	s_nop 0
	global_load_dwordx4 v[8:11], v102, s[0:1] offset:16
	global_load_dwordx4 v[28:31], v102, s[0:1]
	s_mov_b64 s[0:1], 0x2000
	v_lshl_add_u64 v[12:13], v[20:21], 0, s[0:1]
	v_add_co_u32_e64 v14, s[0:1], s97, v20
	s_waitcnt vmcnt(10)
	v_lshlrev_b32_e32 v114, 16, v64
	v_addc_co_u32_e64 v15, s[0:1], 0, v21, s[0:1]
	s_mov_b64 s[0:1], 0x4000
	s_nop 0
	v_lshl_add_u64 v[16:17], v[20:21], 0, s[0:1]
	v_add_co_u32_e64 v18, s[0:1], s53, v20
	global_load_dwordx4 v[32:35], v[14:15], off
	s_nop 0
	global_load_dwordx4 v[12:15], v[12:13], off offset:16
	v_addc_co_u32_e64 v19, s[0:1], 0, v21, s[0:1]
	s_mov_b64 s[0:1], 0x6000
	s_nop 0
	v_lshl_add_u64 v[22:23], v[20:21], 0, s[0:1]
	s_movk_i32 s0, 0x6000
	v_add_co_u32_e64 v20, s[0:1], s0, v20
	global_load_dwordx4 v[36:39], v[18:19], off
	s_nop 0
	global_load_dwordx4 v[16:19], v[16:17], off offset:16
	v_addc_co_u32_e64 v21, s[0:1], 0, v21, s[0:1]
	global_load_dwordx4 v[40:43], v[20:21], off
	s_nop 0
	global_load_dwordx4 v[20:23], v[22:23], off offset:16
	s_lshl_b64 s[98:99], s[8:9], 1
	v_readlane_b32 s100, v252, 36
	v_readlane_b32 s101, v252, 37
	s_add_u32 s98, s100, s98
	s_addc_u32 s99, s101, s99
	s_lshl_b32 s100, s12, 1
	s_add_u32 s98, s98, s100
	s_addc_u32 s99, s99, 0
	v_lshlrev_b32_e32 v226, 1, v3
	v_mov_b32_e32 v227, 0
	v_lshl_add_u64 v[192:193], s[98:99], 0, v[226:227]
	s_and_saveexec_b64 s[100:101], vcc
	v_lshlrev_b64 v[228:229], 11, v[80:81]
	v_lshl_add_u64 v[228:229], v[192:193], 0, v[228:229]
	global_load_dwordx4 v[132:135], v[228:229], off
	s_or_b64 exec, exec, s[100:101]
	s_and_saveexec_b64 s[100:101], s[4:5]
	v_lshlrev_b64 v[228:229], 11, v[82:83]
	v_lshl_add_u64 v[228:229], v[192:193], 0, v[228:229]
	global_load_dwordx4 v[136:139], v[228:229], off
	s_or_b64 exec, exec, s[100:101]
	s_and_saveexec_b64 s[100:101], s[6:7]
	v_lshlrev_b64 v[228:229], 11, v[84:85]
	v_lshl_add_u64 v[228:229], v[192:193], 0, v[228:229]
	global_load_dwordx4 v[140:143], v[228:229], off
	s_or_b64 exec, exec, s[100:101]
	v_lshl_add_u64 v[228:229], v[192:193], 0, v[86:87]
	global_load_dwordx4 v[144:147], v[228:229], off
	v_lshl_add_u64 v[228:229], v[192:193], 0, v[88:89]
	global_load_dwordx4 v[148:151], v[228:229], off
	v_lshl_add_u64 v[228:229], v[192:193], 0, v[90:91]
	global_load_dwordx4 v[152:155], v[228:229], off
	v_lshl_add_u64 v[228:229], v[192:193], 0, v[92:93]
	global_load_dwordx4 v[156:159], v[228:229], off
	v_lshl_add_u64 v[228:229], v[192:193], 0, v[94:95]
	global_load_dwordx4 v[160:163], v[228:229], off
	v_lshl_add_u64 v[228:229], v[192:193], 0, v[96:97]
	global_load_dwordx4 v[164:167], v[228:229], off
	v_lshl_add_u64 v[228:229], v[192:193], 0, v[98:99]
	global_load_dwordx4 v[168:171], v[228:229], off
	v_lshl_add_u64 v[228:229], v[192:193], 0, v[100:101]
	global_load_dwordx4 v[172:175], v[228:229], off
	v_readlane_b32 s98, v255, 19
	v_readlane_b32 s99, v255, 21
	v_mov_b32_e32 v224, v102
	v_mov_b32_e32 v225, 0
	s_add_u32 s98, s98, s11
	s_addc_u32 s99, s99, 0
	global_load_dwordx4 v[176:179], v102, s[98:99] offset:16
	global_load_dwordx4 v[180:183], v102, s[98:99]
	v_lshl_add_u64 v[222:223], s[98:99], 0, v[224:225]
	s_mov_b32 s100, s97
	s_mov_b32 s101, 0
	v_lshl_add_u64 v[228:229], v[222:223], 0, s[100:101]
	global_load_dwordx4 v[184:187], v[228:229], off
	s_mov_b64 s[100:101], 0x2000
	v_lshl_add_u64 v[228:229], v[222:223], 0, s[100:101]
	global_load_dwordx4 v[188:191], v[228:229], off offset:16
	s_mov_b32 s100, s53
	s_mov_b32 s101, 0
	v_lshl_add_u64 v[228:229], v[222:223], 0, s[100:101]
	global_load_dwordx4 v[206:209], v[228:229], off
	s_mov_b64 s[100:101], 0x4000
	v_lshl_add_u64 v[228:229], v[222:223], 0, s[100:101]
	global_load_dwordx4 v[210:213], v[228:229], off offset:16
	s_mov_b64 s[100:101], 0x6000
	v_lshl_add_u64 v[228:229], v[222:223], 0, s[100:101]
	global_load_dwordx4 v[214:217], v[228:229], off
	global_load_dwordx4 v[218:221], v[228:229], off offset:16
	v_and_b32_e32 v115, 0xffff0000, v64
	v_lshlrev_b32_e32 v116, 16, v68
	v_and_b32_e32 v117, 0xffff0000, v68
	v_lshlrev_b32_e32 v112, 16, v72
	v_and_b32_e32 v113, 0xffff0000, v72
	v_lshlrev_b32_e32 v122, 16, v65
	v_and_b32_e32 v123, 0xffff0000, v65
	v_lshlrev_b32_e32 v68, 16, v69
	v_and_b32_e32 v69, 0xffff0000, v69
	v_lshlrev_b32_e32 v72, 16, v73
	v_and_b32_e32 v73, 0xffff0000, v73
	s_waitcnt vmcnt(34)
; __device__ __forceinline__ float fsigmoid(float x) { return __builtin_amdgcn_rcpf(1.0f + __expf(-x)); }
; #define LAS __attribute__((address_space(3)))
; __device__ __forceinline__ void load_conv(LAS char* dst, const bf16_t* src, int pos0, const float* cw  , const LAS float* rowscale, float cscale, int tid) {
;     ...
;     float u[3][8];
; #pragma unroll
;     for (int j = 0; j < 3; ++j) unpack8(rw[j], u[j]);
; #pragma unroll
;     for (int r = 0; r < 8; ++r) {
;         float x[8]; unpack8(rw[3 + r], x);
;         const float sc = sc8[r];
;         float o[8];
; #pragma unroll
;         for (int e = 0; e < 8; ++e) { const float cv = (w[0][e] * u[0][e] + w[1][e] * u[1][e]) + (w[2][e] * u[2][e] + w[3][e] * x[e]); o[e] = cv * fsigmoid(cv) * sc;
;             u[0][e] = u[1][e]; u[1][e] = u[2][e]; u[2][e] = x[e]; }
;         *(LAS u32x4*)(dst + (r0 + r) * PIT + cg * 16) = pack8(o);
	v_lshlrev_b32_e32 v108, 16, v76
	v_and_b32_e32 v109, 0xffff0000, v76
	v_and_b32_e32 v65, 0xffff0000, v77
	s_mov_b32 s14, 0x3d800000
	v_lshlrev_b32_e32 v124, 16, v70
	v_and_b32_e32 v125, 0xffff0000, v70
	v_lshlrev_b32_e32 v120, 16, v74
	v_and_b32_e32 v121, 0xffff0000, v74
	v_lshlrev_b32_e32 v130, 16, v71
	v_and_b32_e32 v131, 0xffff0000, v71
	v_lshlrev_b32_e32 v70, 16, v75
	v_and_b32_e32 v71, 0xffff0000, v75
	s_movk_i32 s0, 0x220
	v_add_u32_e32 v103, 0, v0
	v_mul_lo_u32 v107, v110, s0
	v_add_u32_e32 v105, v103, v107
	s_waitcnt vmcnt(33)
	v_lshlrev_b32_e32 v110, 16, v63
	v_and_b32_e32 v111, 0xffff0000, v63
	v_mul_lo_u32 v106, v106, s0
	s_lshl_b64 s[68:69], s[8:9], 1
	v_readlane_b32 s0, v252, 36
	s_add_u32 s0, s0, s68
	v_readlane_b32 s1, v252, 37
	s_addc_u32 s1, s1, s69
	s_lshl_b32 s84, s12, 1
	s_add_u32 s0, s0, s84
	s_addc_u32 s1, s1, 0
	s_movk_i32 s13, 0x220
	s_waitcnt vmcnt(24)
	v_pk_mul_f32 v[118:119], v[32:33], v[114:115]
	s_nop 0
	v_pk_fma_f32 v[116:117], v[28:29], v[116:117], v[118:119]
	s_waitcnt vmcnt(20)
	v_pk_mul_f32 v[118:119], v[40:41], v[108:109]
	s_nop 0
	v_pk_fma_f32 v[118:119], v[36:37], v[112:113], v[118:119]
	s_nop 0
	v_pk_add_f32 v[116:117], v[116:117], v[118:119]
	s_nop 0
	v_mul_f32_e32 v64, 0xbfb8aa3b, v116
	v_exp_f32_e32 v64, v64
	s_nop 0
	v_add_f32_e32 v64, 1.0, v64
	v_rcp_f32_e32 v118, v64
	v_mul_f32_e32 v64, 0xbfb8aa3b, v117
	v_exp_f32_e32 v64, v64
	s_nop 0
	v_add_f32_e32 v64, 1.0, v64
	v_rcp_f32_e32 v119, v64
	v_lshlrev_b32_e32 v64, 16, v77
	v_pk_mul_f32 v[76:77], v[34:35], v[122:123]
	v_pk_mul_f32 v[116:117], v[116:117], v[118:119]
	v_pk_fma_f32 v[68:69], v[30:31], v[68:69], v[76:77]
	v_pk_mul_f32 v[76:77], v[42:43], v[64:65]
	v_pk_mul_f32 v[116:117], v[116:117], s[14:15] op_sel_hi:[1,0]
	v_pk_fma_f32 v[76:77], v[38:39], v[72:73], v[76:77]
	v_cvt_pk_bf16_f32 v116, v116, v117
	v_pk_add_f32 v[68:69], v[68:69], v[76:77]
	s_nop 0
	v_mul_f32_e32 v76, 0xbfb8aa3b, v68
	v_mul_f32_e32 v77, 0xbfb8aa3b, v69
	v_exp_f32_e32 v76, v76
	v_exp_f32_e32 v77, v77
	v_add_f32_e32 v76, 1.0, v76
	v_add_f32_e32 v77, 1.0, v77
	v_rcp_f32_e32 v76, v76
	v_rcp_f32_e32 v77, v77
	s_nop 0
	v_pk_mul_f32 v[68:69], v[68:69], v[76:77]
	v_lshlrev_b32_e32 v76, 16, v66
	v_and_b32_e32 v77, 0xffff0000, v66
	v_pk_mul_f32 v[118:119], v[68:69], s[14:15] op_sel_hi:[1,0]
	v_lshlrev_b32_e32 v68, 16, v78
	v_and_b32_e32 v69, 0xffff0000, v78
	v_pk_mul_f32 v[128:129], v[12:13], v[76:77]
	v_cvt_pk_bf16_f32 v117, v118, v119
	v_pk_fma_f32 v[124:125], v[8:9], v[124:125], v[128:129]
	s_waitcnt vmcnt(19)
	v_pk_mul_f32 v[128:129], v[20:21], v[68:69]
	s_nop 0
	v_pk_fma_f32 v[128:129], v[16:17], v[120:121], v[128:129]
	s_nop 0
	v_pk_add_f32 v[124:125], v[124:125], v[128:129]
	s_nop 0
	v_mul_f32_e32 v66, 0xbfb8aa3b, v124
	v_exp_f32_e32 v66, v66
	s_nop 0
	v_add_f32_e32 v66, 1.0, v66
	v_rcp_f32_e32 v128, v66
	v_mul_f32_e32 v66, 0xbfb8aa3b, v125
	v_exp_f32_e32 v66, v66
	s_nop 0
	v_add_f32_e32 v66, 1.0, v66
	v_rcp_f32_e32 v129, v66
	v_lshlrev_b32_e32 v66, 16, v79
	v_pk_mul_f32 v[124:125], v[124:125], v[128:129]
	s_nop 0
	v_pk_mul_f32 v[128:129], v[124:125], s[14:15] op_sel_hi:[1,0]
	v_lshlrev_b32_e32 v124, 16, v67
	v_and_b32_e32 v125, 0xffff0000, v67
	v_and_b32_e32 v67, 0xffff0000, v79
	v_pk_mul_f32 v[74:75], v[14:15], v[124:125]
	v_pk_mul_f32 v[78:79], v[22:23], v[66:67]
	v_pk_fma_f32 v[74:75], v[10:11], v[130:131], v[74:75]
	v_pk_fma_f32 v[78:79], v[18:19], v[70:71], v[78:79]
	v_cvt_pk_bf16_f32 v118, v128, v129
	v_pk_add_f32 v[74:75], v[74:75], v[78:79]
	s_nop 0
	v_mul_f32_e32 v78, 0xbfb8aa3b, v74
	v_mul_f32_e32 v79, 0xbfb8aa3b, v75
	v_exp_f32_e32 v78, v78
	v_exp_f32_e32 v79, v79
	v_add_f32_e32 v78, 1.0, v78
	v_add_f32_e32 v79, 1.0, v79
	v_rcp_f32_e32 v78, v78
	v_rcp_f32_e32 v79, v79
	s_nop 0
	v_pk_mul_f32 v[74:75], v[74:75], v[78:79]
	s_nop 0
	v_pk_mul_f32 v[74:75], v[74:75], s[14:15] op_sel_hi:[1,0]
	s_nop 0
	v_cvt_pk_bf16_f32 v119, v74, v75
	ds_write_b128 v105, v[116:119]
	v_lshlrev_b32_e32 v118, 16, v60
	v_and_b32_e32 v119, 0xffff0000, v60
	v_pk_mul_f32 v[74:75], v[32:33], v[112:113]
	v_pk_mul_f32 v[78:79], v[40:41], v[118:119]
	v_pk_fma_f32 v[74:75], v[28:29], v[114:115], v[74:75]
	v_pk_fma_f32 v[78:79], v[36:37], v[108:109], v[78:79]
	v_lshlrev_b32_e32 v116, 16, v61
	v_pk_add_f32 v[74:75], v[74:75], v[78:79]
	v_and_b32_e32 v117, 0xffff0000, v61
	v_mul_f32_e32 v60, 0xbfb8aa3b, v74
	v_exp_f32_e32 v60, v60
	v_lshlrev_b32_e32 v114, 16, v62
	v_and_b32_e32 v115, 0xffff0000, v62
	v_add_f32_e32 v60, 1.0, v60
	v_rcp_f32_e32 v78, v60
	v_mul_f32_e32 v60, 0xbfb8aa3b, v75
	v_exp_f32_e32 v60, v60
	s_nop 0
	v_add_f32_e32 v60, 1.0, v60
	v_rcp_f32_e32 v79, v60
	v_pk_mul_f32 v[60:61], v[34:35], v[72:73]
	v_pk_mul_f32 v[74:75], v[74:75], v[78:79]
	v_pk_mul_f32 v[78:79], v[42:43], v[116:117]
	v_pk_fma_f32 v[60:61], v[30:31], v[122:123], v[60:61]
	v_pk_fma_f32 v[78:79], v[38:39], v[64:65], v[78:79]
	v_pk_mul_f32 v[74:75], v[74:75], s[14:15] op_sel_hi:[1,0]
	v_pk_add_f32 v[60:61], v[60:61], v[78:79]
	s_nop 0
	v_mul_f32_e32 v78, 0xbfb8aa3b, v60
	v_mul_f32_e32 v79, 0xbfb8aa3b, v61
	v_exp_f32_e32 v78, v78
	v_exp_f32_e32 v79, v79
	v_add_f32_e32 v78, 1.0, v78
	v_add_f32_e32 v79, 1.0, v79
	v_rcp_f32_e32 v78, v78
	v_rcp_f32_e32 v79, v79
	s_nop 0
	v_pk_mul_f32 v[60:61], v[60:61], v[78:79]
	s_nop 0
	v_pk_mul_f32 v[78:79], v[60:61], s[14:15] op_sel_hi:[1,0]
	v_pk_mul_f32 v[60:61], v[12:13], v[120:121]
	s_nop 0
	v_pk_fma_f32 v[60:61], v[8:9], v[76:77], v[60:61]
	v_pk_mul_f32 v[76:77], v[20:21], v[114:115]
	s_nop 0
	v_pk_fma_f32 v[76:77], v[16:17], v[68:69], v[76:77]
	s_nop 0
	v_pk_add_f32 v[60:61], v[60:61], v[76:77]
	s_nop 0
	v_mul_f32_e32 v62, 0xbfb8aa3b, v60
	v_exp_f32_e32 v62, v62
	s_nop 0
; __device__ __forceinline__ float fsigmoid(float x) { return __builtin_amdgcn_rcpf(1.0f + __expf(-x)); }
; #define LAS __attribute__((address_space(3)))
; __device__ __forceinline__ void load_conv(LAS char* dst, const bf16_t* src, int pos0, const float* cw  , const LAS float* rowscale, float cscale, int tid) {
;     ...
;     for (int r = 0; r < 8; ++r) {
;         float x[8]; unpack8(rw[3 + r], x);
;         const float sc = sc8[r];
;         float o[8];
; #pragma unroll
;         for (int e = 0; e < 8; ++e) { const float cv = (w[0][e] * u[0][e] + w[1][e] * u[1][e]) + (w[2][e] * u[2][e] + w[3][e] * x[e]); o[e] = cv * fsigmoid(cv) * sc;
;             u[0][e] = u[1][e]; u[1][e] = u[2][e]; u[2][e] = x[e]; }
;         *(LAS u32x4*)(dst + (r0 + r) * PIT + cg * 16) = pack8(o);
	v_add_f32_e32 v62, 1.0, v62
	v_rcp_f32_e32 v76, v62
	v_mul_f32_e32 v62, 0xbfb8aa3b, v61
	v_exp_f32_e32 v62, v62
	s_nop 0
	v_add_f32_e32 v62, 1.0, v62
	v_rcp_f32_e32 v77, v62
	v_pk_mul_f32 v[62:63], v[22:23], v[110:111]
	v_pk_mul_f32 v[60:61], v[60:61], v[76:77]
	s_nop 0
	v_pk_mul_f32 v[76:77], v[60:61], s[14:15] op_sel_hi:[1,0]
	v_pk_mul_f32 v[60:61], v[14:15], v[70:71]
	v_pk_fma_f32 v[62:63], v[18:19], v[66:67], v[62:63]
	v_pk_fma_f32 v[60:61], v[10:11], v[124:125], v[60:61]
	s_nop 0
	v_pk_add_f32 v[60:61], v[60:61], v[62:63]
	s_nop 0
	v_mul_f32_e32 v62, 0xbfb8aa3b, v60
	v_mul_f32_e32 v63, 0xbfb8aa3b, v61
	v_exp_f32_e32 v62, v62
	v_exp_f32_e32 v63, v63
	v_add_f32_e32 v62, 1.0, v62
	v_add_f32_e32 v63, 1.0, v63
	v_rcp_f32_e32 v62, v62
	v_rcp_f32_e32 v63, v63
	s_nop 0
	v_pk_mul_f32 v[60:61], v[60:61], v[62:63]
	s_nop 0
	v_pk_mul_f32 v[122:123], v[60:61], s[14:15] op_sel_hi:[1,0]
	v_cvt_pk_bf16_f32 v60, v74, v75
	v_cvt_pk_bf16_f32 v61, v78, v79
	v_cvt_pk_bf16_f32 v62, v76, v77
	v_cvt_pk_bf16_f32 v63, v122, v123
	v_lshlrev_b32_e32 v78, 16, v56
	v_and_b32_e32 v79, 0xffff0000, v56
	ds_write_b128 v105, v[60:63] offset:544
	v_pk_mul_f32 v[60:61], v[32:33], v[108:109]
	v_pk_mul_f32 v[62:63], v[40:41], v[78:79]
	v_pk_fma_f32 v[60:61], v[28:29], v[112:113], v[60:61]
	v_pk_fma_f32 v[62:63], v[36:37], v[118:119], v[62:63]
	v_lshlrev_b32_e32 v76, 16, v57
	v_pk_add_f32 v[60:61], v[60:61], v[62:63]
	v_and_b32_e32 v77, 0xffff0000, v57
	v_mul_f32_e32 v56, 0xbfb8aa3b, v60
	v_exp_f32_e32 v56, v56
	v_lshlrev_b32_e32 v74, 16, v58
	v_and_b32_e32 v75, 0xffff0000, v58
	v_add_f32_e32 v56, 1.0, v56
	v_rcp_f32_e32 v62, v56
	v_mul_f32_e32 v56, 0xbfb8aa3b, v61
	v_exp_f32_e32 v56, v56
	s_nop 0
	v_add_f32_e32 v56, 1.0, v56
	v_rcp_f32_e32 v63, v56
	v_pk_mul_f32 v[56:57], v[34:35], v[64:65]
	v_pk_mul_f32 v[60:61], v[60:61], v[62:63]
	v_pk_mul_f32 v[62:63], v[42:43], v[76:77]
	v_pk_fma_f32 v[56:57], v[30:31], v[72:73], v[56:57]
	v_pk_fma_f32 v[62:63], v[38:39], v[116:117], v[62:63]
	v_pk_mul_f32 v[72:73], v[20:21], v[74:75]
	v_pk_add_f32 v[56:57], v[56:57], v[62:63]
	v_pk_fma_f32 v[72:73], v[16:17], v[114:115], v[72:73]
	v_mul_f32_e32 v62, 0xbfb8aa3b, v56
	v_mul_f32_e32 v63, 0xbfb8aa3b, v57
	v_exp_f32_e32 v62, v62
	v_exp_f32_e32 v63, v63
	v_pk_mul_f32 v[60:61], v[60:61], s[14:15] op_sel_hi:[1,0]
	v_add_f32_e32 v62, 1.0, v62
	v_add_f32_e32 v63, 1.0, v63
	v_rcp_f32_e32 v62, v62
	v_rcp_f32_e32 v63, v63
	s_nop 0
	v_pk_mul_f32 v[56:57], v[56:57], v[62:63]
	s_nop 0
	v_pk_mul_f32 v[62:63], v[56:57], s[14:15] op_sel_hi:[1,0]
	v_pk_mul_f32 v[56:57], v[12:13], v[68:69]
	s_nop 0
	v_pk_fma_f32 v[56:57], v[8:9], v[120:121], v[56:57]
	s_nop 0
	v_pk_add_f32 v[56:57], v[56:57], v[72:73]
	s_nop 0
	v_mul_f32_e32 v58, 0xbfb8aa3b, v56
	v_exp_f32_e32 v58, v58
	s_nop 0
	v_add_f32_e32 v58, 1.0, v58
	v_rcp_f32_e32 v72, v58
	v_mul_f32_e32 v58, 0xbfb8aa3b, v57
	v_exp_f32_e32 v58, v58
	s_nop 0
	v_add_f32_e32 v58, 1.0, v58
	v_rcp_f32_e32 v73, v58
	s_nop 0
	v_pk_mul_f32 v[56:57], v[56:57], v[72:73]
	v_lshlrev_b32_e32 v72, 16, v59
	v_and_b32_e32 v73, 0xffff0000, v59
	v_pk_mul_f32 v[112:113], v[56:57], s[14:15] op_sel_hi:[1,0]
	v_pk_mul_f32 v[56:57], v[14:15], v[66:67]
	v_pk_mul_f32 v[58:59], v[22:23], v[72:73]
	v_pk_fma_f32 v[56:57], v[10:11], v[70:71], v[56:57]
	v_pk_fma_f32 v[58:59], v[18:19], v[110:111], v[58:59]
	s_nop 0
	v_pk_add_f32 v[56:57], v[56:57], v[58:59]
	s_nop 0
	v_mul_f32_e32 v58, 0xbfb8aa3b, v56
	v_mul_f32_e32 v59, 0xbfb8aa3b, v57
	v_exp_f32_e32 v58, v58
	v_exp_f32_e32 v59, v59
	v_add_f32_e32 v58, 1.0, v58
	v_add_f32_e32 v59, 1.0, v59
	v_rcp_f32_e32 v58, v58
	v_rcp_f32_e32 v59, v59
	s_nop 0
	v_pk_mul_f32 v[56:57], v[56:57], v[58:59]
	s_nop 0
	v_pk_mul_f32 v[70:71], v[56:57], s[14:15] op_sel_hi:[1,0]
	v_cvt_pk_bf16_f32 v56, v60, v61
	v_cvt_pk_bf16_f32 v57, v62, v63
	v_cvt_pk_bf16_f32 v58, v112, v113
	v_cvt_pk_bf16_f32 v59, v70, v71
	v_lshlrev_b32_e32 v70, 16, v52
	v_and_b32_e32 v71, 0xffff0000, v52
	ds_write_b128 v105, v[56:59] offset:1088
	v_pk_mul_f32 v[56:57], v[32:33], v[118:119]
	v_pk_mul_f32 v[58:59], v[40:41], v[70:71]
	v_pk_fma_f32 v[56:57], v[28:29], v[108:109], v[56:57]
	v_pk_fma_f32 v[58:59], v[36:37], v[78:79], v[58:59]
	v_lshlrev_b32_e32 v62, 16, v53
	v_pk_add_f32 v[56:57], v[56:57], v[58:59]
	v_and_b32_e32 v63, 0xffff0000, v53
	v_mul_f32_e32 v52, 0xbfb8aa3b, v56
	v_exp_f32_e32 v52, v52
	v_lshlrev_b32_e32 v60, 16, v54
	v_and_b32_e32 v61, 0xffff0000, v54
	v_add_f32_e32 v52, 1.0, v52
	v_rcp_f32_e32 v58, v52
	v_mul_f32_e32 v52, 0xbfb8aa3b, v57
	v_exp_f32_e32 v52, v52
	s_nop 0
	v_add_f32_e32 v52, 1.0, v52
	v_rcp_f32_e32 v59, v52
	v_pk_mul_f32 v[52:53], v[34:35], v[116:117]
	v_pk_mul_f32 v[56:57], v[56:57], v[58:59]
	v_pk_mul_f32 v[58:59], v[42:43], v[62:63]
	v_pk_fma_f32 v[52:53], v[30:31], v[64:65], v[52:53]
	v_pk_fma_f32 v[58:59], v[38:39], v[76:77], v[58:59]
	v_pk_mul_f32 v[56:57], v[56:57], s[14:15] op_sel_hi:[1,0]
	v_pk_add_f32 v[52:53], v[52:53], v[58:59]
	s_nop 0
	v_mul_f32_e32 v58, 0xbfb8aa3b, v52
	v_mul_f32_e32 v59, 0xbfb8aa3b, v53
	v_exp_f32_e32 v58, v58
	v_exp_f32_e32 v59, v59
	v_add_f32_e32 v58, 1.0, v58
	v_add_f32_e32 v59, 1.0, v59
	v_rcp_f32_e32 v58, v58
	v_rcp_f32_e32 v59, v59
	s_nop 0
	v_pk_mul_f32 v[52:53], v[52:53], v[58:59]
	s_nop 0
	v_pk_mul_f32 v[64:65], v[52:53], s[14:15] op_sel_hi:[1,0]
	v_pk_mul_f32 v[52:53], v[12:13], v[114:115]
	v_pk_mul_f32 v[58:59], v[20:21], v[60:61]
	v_pk_fma_f32 v[52:53], v[8:9], v[68:69], v[52:53]
	v_pk_fma_f32 v[58:59], v[16:17], v[74:75], v[58:59]
	s_nop 0
	v_pk_add_f32 v[52:53], v[52:53], v[58:59]
	s_nop 0
	v_mul_f32_e32 v54, 0xbfb8aa3b, v52
	v_exp_f32_e32 v54, v54
	s_nop 0
	v_add_f32_e32 v54, 1.0, v54
	v_rcp_f32_e32 v58, v54
; __device__ __forceinline__ float fsigmoid(float x) { return __builtin_amdgcn_rcpf(1.0f + __expf(-x)); }
; #define LAS __attribute__((address_space(3)))
; __device__ __forceinline__ void load_conv(LAS char* dst, const bf16_t* src, int pos0, const float* cw  , const LAS float* rowscale, float cscale, int tid) {
;     ...
;     for (int r = 0; r < 8; ++r) {
;         float x[8]; unpack8(rw[3 + r], x);
;         const float sc = sc8[r];
;         float o[8];
; #pragma unroll
;         for (int e = 0; e < 8; ++e) { const float cv = (w[0][e] * u[0][e] + w[1][e] * u[1][e]) + (w[2][e] * u[2][e] + w[3][e] * x[e]); o[e] = cv * fsigmoid(cv) * sc;
;             u[0][e] = u[1][e]; u[1][e] = u[2][e]; u[2][e] = x[e]; }
;         *(LAS u32x4*)(dst + (r0 + r) * PIT + cg * 16) = pack8(o);
	v_mul_f32_e32 v54, 0xbfb8aa3b, v53
	v_exp_f32_e32 v54, v54
	s_nop 0
	v_add_f32_e32 v54, 1.0, v54
	v_rcp_f32_e32 v59, v54
	s_nop 0
	v_pk_mul_f32 v[52:53], v[52:53], v[58:59]
	v_lshlrev_b32_e32 v58, 16, v55
	v_and_b32_e32 v59, 0xffff0000, v55
	v_pk_mul_f32 v[68:69], v[52:53], s[14:15] op_sel_hi:[1,0]
	v_pk_mul_f32 v[52:53], v[14:15], v[110:111]
	v_pk_mul_f32 v[54:55], v[22:23], v[58:59]
	v_pk_fma_f32 v[52:53], v[10:11], v[66:67], v[52:53]
	v_pk_fma_f32 v[54:55], v[18:19], v[72:73], v[54:55]
	s_nop 0
	v_pk_add_f32 v[52:53], v[52:53], v[54:55]
	s_nop 0
	v_mul_f32_e32 v54, 0xbfb8aa3b, v52
	v_mul_f32_e32 v55, 0xbfb8aa3b, v53
	v_exp_f32_e32 v54, v54
	v_exp_f32_e32 v55, v55
	v_add_f32_e32 v54, 1.0, v54
	v_add_f32_e32 v55, 1.0, v55
	v_rcp_f32_e32 v54, v54
	v_rcp_f32_e32 v55, v55
	s_nop 0
	v_pk_mul_f32 v[52:53], v[52:53], v[54:55]
	s_nop 0
	v_pk_mul_f32 v[66:67], v[52:53], s[14:15] op_sel_hi:[1,0]
	v_cvt_pk_bf16_f32 v52, v56, v57
	v_cvt_pk_bf16_f32 v53, v64, v65
	v_cvt_pk_bf16_f32 v54, v68, v69
	v_cvt_pk_bf16_f32 v55, v66, v67
	v_lshlrev_b32_e32 v56, 16, v48
	v_and_b32_e32 v57, 0xffff0000, v48
	ds_write_b128 v105, v[52:55] offset:1632
	v_pk_mul_f32 v[52:53], v[32:33], v[78:79]
	v_pk_mul_f32 v[54:55], v[40:41], v[56:57]
	v_pk_fma_f32 v[52:53], v[28:29], v[118:119], v[52:53]
	v_pk_fma_f32 v[54:55], v[36:37], v[70:71], v[54:55]
	s_nop 0
	v_pk_add_f32 v[52:53], v[52:53], v[54:55]
	s_nop 0
	v_mul_f32_e32 v48, 0xbfb8aa3b, v52
	v_exp_f32_e32 v48, v48
	s_nop 0
	v_add_f32_e32 v48, 1.0, v48
	v_rcp_f32_e32 v54, v48
	v_mul_f32_e32 v48, 0xbfb8aa3b, v53
	v_exp_f32_e32 v48, v48
	s_nop 0
	v_add_f32_e32 v48, 1.0, v48
	v_rcp_f32_e32 v55, v48
	s_nop 0
	v_pk_mul_f32 v[52:53], v[52:53], v[54:55]
	v_lshlrev_b32_e32 v54, 16, v49
	v_and_b32_e32 v55, 0xffff0000, v49
	v_pk_mul_f32 v[64:65], v[52:53], s[14:15] op_sel_hi:[1,0]
	v_pk_mul_f32 v[48:49], v[34:35], v[76:77]
	v_pk_mul_f32 v[52:53], v[42:43], v[54:55]
	v_pk_fma_f32 v[48:49], v[30:31], v[116:117], v[48:49]
	v_pk_fma_f32 v[52:53], v[38:39], v[62:63], v[52:53]
	v_cvt_pk_bf16_f32 v64, v64, v65
	v_pk_add_f32 v[48:49], v[48:49], v[52:53]
	s_nop 0
	v_mul_f32_e32 v52, 0xbfb8aa3b, v48
	v_mul_f32_e32 v53, 0xbfb8aa3b, v49
	v_exp_f32_e32 v52, v52
	v_exp_f32_e32 v53, v53
	v_add_f32_e32 v52, 1.0, v52
	v_add_f32_e32 v53, 1.0, v53
	v_rcp_f32_e32 v52, v52
	v_rcp_f32_e32 v53, v53
	s_nop 0
	v_pk_mul_f32 v[48:49], v[48:49], v[52:53]
	v_lshlrev_b32_e32 v52, 16, v50
	v_and_b32_e32 v53, 0xffff0000, v50
	v_pk_mul_f32 v[66:67], v[48:49], s[14:15] op_sel_hi:[1,0]
	v_pk_mul_f32 v[48:49], v[12:13], v[74:75]
	v_pk_mul_f32 v[68:69], v[20:21], v[52:53]
	v_pk_fma_f32 v[48:49], v[8:9], v[114:115], v[48:49]
	v_pk_fma_f32 v[68:69], v[16:17], v[60:61], v[68:69]
	v_cvt_pk_bf16_f32 v65, v66, v67
	v_pk_add_f32 v[48:49], v[48:49], v[68:69]
	s_nop 0
	v_mul_f32_e32 v50, 0xbfb8aa3b, v48
	v_exp_f32_e32 v50, v50
	s_nop 0
	v_add_f32_e32 v50, 1.0, v50
	v_rcp_f32_e32 v68, v50
	v_mul_f32_e32 v50, 0xbfb8aa3b, v49
	v_exp_f32_e32 v50, v50
	s_nop 0
	v_add_f32_e32 v50, 1.0, v50
	v_rcp_f32_e32 v69, v50
	s_nop 0
	v_pk_mul_f32 v[48:49], v[48:49], v[68:69]
	s_nop 0
	v_pk_mul_f32 v[68:69], v[48:49], s[14:15] op_sel_hi:[1,0]
	v_lshlrev_b32_e32 v48, 16, v51
	v_and_b32_e32 v49, 0xffff0000, v51
	v_pk_mul_f32 v[50:51], v[14:15], v[72:73]
	v_pk_mul_f32 v[108:109], v[22:23], v[48:49]
	v_pk_fma_f32 v[50:51], v[10:11], v[110:111], v[50:51]
	v_pk_fma_f32 v[108:109], v[18:19], v[58:59], v[108:109]
	v_cvt_pk_bf16_f32 v66, v68, v69
	v_pk_add_f32 v[50:51], v[50:51], v[108:109]
	s_nop 0
	v_mul_f32_e32 v108, 0xbfb8aa3b, v50
	v_mul_f32_e32 v109, 0xbfb8aa3b, v51
	v_exp_f32_e32 v108, v108
	v_exp_f32_e32 v109, v109
	v_add_f32_e32 v108, 1.0, v108
	v_add_f32_e32 v109, 1.0, v109
	v_rcp_f32_e32 v108, v108
	v_rcp_f32_e32 v109, v109
	s_nop 0
	v_pk_mul_f32 v[50:51], v[50:51], v[108:109]
	s_nop 0
	v_pk_mul_f32 v[50:51], v[50:51], s[14:15] op_sel_hi:[1,0]
	s_nop 0
	v_cvt_pk_bf16_f32 v67, v50, v51
	ds_write_b128 v105, v[64:67] offset:2176
	v_lshlrev_b32_e32 v66, 16, v44
	v_and_b32_e32 v67, 0xffff0000, v44
	v_pk_mul_f32 v[50:51], v[32:33], v[70:71]
	v_pk_mul_f32 v[64:65], v[40:41], v[66:67]
	v_pk_fma_f32 v[50:51], v[28:29], v[78:79], v[50:51]
	v_pk_fma_f32 v[64:65], v[36:37], v[56:57], v[64:65]
	s_nop 0
	v_pk_add_f32 v[50:51], v[50:51], v[64:65]
	s_nop 0
	v_mul_f32_e32 v44, 0xbfb8aa3b, v50
	v_exp_f32_e32 v44, v44
	s_nop 0
	v_add_f32_e32 v44, 1.0, v44
	v_rcp_f32_e32 v64, v44
	v_mul_f32_e32 v44, 0xbfb8aa3b, v51
	v_exp_f32_e32 v44, v44
	s_nop 0
	v_add_f32_e32 v44, 1.0, v44
	v_rcp_f32_e32 v65, v44
	s_nop 0
	v_pk_mul_f32 v[50:51], v[50:51], v[64:65]
	v_lshlrev_b32_e32 v64, 16, v45
	v_and_b32_e32 v65, 0xffff0000, v45
	v_pk_mul_f32 v[68:69], v[50:51], s[14:15] op_sel_hi:[1,0]
	v_pk_mul_f32 v[44:45], v[34:35], v[62:63]
	v_pk_mul_f32 v[50:51], v[42:43], v[64:65]
	v_pk_fma_f32 v[44:45], v[30:31], v[76:77], v[44:45]
	v_pk_fma_f32 v[50:51], v[38:39], v[54:55], v[50:51]
	s_nop 0
	v_pk_add_f32 v[44:45], v[44:45], v[50:51]
	s_nop 0
	v_mul_f32_e32 v50, 0xbfb8aa3b, v44
	v_mul_f32_e32 v51, 0xbfb8aa3b, v45
	v_exp_f32_e32 v50, v50
	v_exp_f32_e32 v51, v51
	v_add_f32_e32 v50, 1.0, v50
	v_add_f32_e32 v51, 1.0, v51
	v_rcp_f32_e32 v50, v50
	v_rcp_f32_e32 v51, v51
	s_nop 0
	v_pk_mul_f32 v[44:45], v[44:45], v[50:51]
	s_nop 0
	v_pk_mul_f32 v[76:77], v[44:45], s[14:15] op_sel_hi:[1,0]
	v_lshlrev_b32_e32 v50, 16, v46
	v_and_b32_e32 v51, 0xffff0000, v46
	v_pk_mul_f32 v[44:45], v[12:13], v[60:61]
	s_nop 0
	v_pk_fma_f32 v[44:45], v[8:9], v[74:75], v[44:45]
	v_pk_mul_f32 v[74:75], v[20:21], v[50:51]
	s_nop 0
	v_pk_fma_f32 v[74:75], v[16:17], v[52:53], v[74:75]
	s_nop 0
	v_pk_add_f32 v[44:45], v[44:45], v[74:75]
	s_nop 0
; __device__ __forceinline__ float fsigmoid(float x) { return __builtin_amdgcn_rcpf(1.0f + __expf(-x)); }
; #define LAS __attribute__((address_space(3)))
; __device__ __forceinline__ void load_conv(LAS char* dst, const bf16_t* src, int pos0, const float* cw  , const LAS float* rowscale, float cscale, int tid) {
;     const int cg = tid & 31, rs = tid >> 5, r0 = rs * 8;
;     u32x4 rw[11];
; #pragma unroll
;     for (int j = 0; j < 11; ++j) { const int rr = r0 - 3 + j;
;         if (j >= 3 || pos0 + rr >= 0) rw[j] = *(const u32x4*)(src + (ptrdiff_t)rr * PP + cg * 8); else rw[j] = (u32x4){0u, 0u, 0u, 0u}; }
;     ...
;     for (int r = 0; r < 8; ++r) {
;         float x[8]; unpack8(rw[3 + r], x);
;         const float sc = sc8[r];
;         float o[8];
; #pragma unroll
;         for (int e = 0; e < 8; ++e) { const float cv = (w[0][e] * u[0][e] + w[1][e] * u[1][e]) + (w[2][e] * u[2][e] + w[3][e] * x[e]); o[e] = cv * fsigmoid(cv) * sc;
;             u[0][e] = u[1][e]; u[1][e] = u[2][e]; u[2][e] = x[e]; }
;         *(LAS u32x4*)(dst + (r0 + r) * PIT + cg * 16) = pack8(o);
	v_mul_f32_e32 v46, 0xbfb8aa3b, v44
	v_exp_f32_e32 v46, v46
	s_nop 0
	v_add_f32_e32 v46, 1.0, v46
	v_rcp_f32_e32 v74, v46
	v_mul_f32_e32 v46, 0xbfb8aa3b, v45
	v_exp_f32_e32 v46, v46
	s_nop 0
	v_add_f32_e32 v46, 1.0, v46
	v_rcp_f32_e32 v75, v46
	s_nop 0
	v_pk_mul_f32 v[44:45], v[44:45], v[74:75]
	s_nop 0
	v_pk_mul_f32 v[74:75], v[44:45], s[14:15] op_sel_hi:[1,0]
	v_lshlrev_b32_e32 v44, 16, v47
	v_and_b32_e32 v45, 0xffff0000, v47
	v_pk_mul_f32 v[46:47], v[14:15], v[58:59]
	v_cvt_pk_bf16_f32 v74, v74, v75
	v_pk_fma_f32 v[46:47], v[10:11], v[72:73], v[46:47]
	v_pk_mul_f32 v[72:73], v[22:23], v[44:45]
	s_nop 0
	v_pk_fma_f32 v[72:73], v[18:19], v[48:49], v[72:73]
	s_nop 0
	v_pk_add_f32 v[46:47], v[46:47], v[72:73]
	s_nop 0
	v_mul_f32_e32 v72, 0xbfb8aa3b, v46
	v_mul_f32_e32 v73, 0xbfb8aa3b, v47
	v_exp_f32_e32 v72, v72
	v_exp_f32_e32 v73, v73
	v_add_f32_e32 v72, 1.0, v72
	v_add_f32_e32 v73, 1.0, v73
	v_rcp_f32_e32 v72, v72
	v_rcp_f32_e32 v73, v73
	s_nop 0
	v_pk_mul_f32 v[46:47], v[46:47], v[72:73]
	s_nop 0
	v_pk_mul_f32 v[46:47], v[46:47], s[14:15] op_sel_hi:[1,0]
	v_cvt_pk_bf16_f32 v72, v68, v69
	v_cvt_pk_bf16_f32 v75, v46, v47
	v_lshlrev_b32_e32 v46, 16, v24
	v_and_b32_e32 v47, 0xffff0000, v24
	v_pk_mul_f32 v[68:69], v[32:33], v[56:57]
	v_cvt_pk_bf16_f32 v73, v76, v77
	v_pk_fma_f32 v[68:69], v[28:29], v[70:71], v[68:69]
	v_pk_mul_f32 v[70:71], v[40:41], v[46:47]
	ds_write_b128 v105, v[72:75] offset:2720
	v_pk_fma_f32 v[70:71], v[36:37], v[66:67], v[70:71]
	v_lshlrev_b32_e32 v72, 16, v26
	v_pk_add_f32 v[68:69], v[68:69], v[70:71]
	v_and_b32_e32 v73, 0xffff0000, v26
	v_mul_f32_e32 v24, 0xbfb8aa3b, v68
	v_exp_f32_e32 v24, v24
	v_lshlrev_b32_e32 v74, 16, v27
	v_and_b32_e32 v75, 0xffff0000, v27
	v_add_f32_e32 v24, 1.0, v24
	v_rcp_f32_e32 v70, v24
	v_mul_f32_e32 v24, 0xbfb8aa3b, v69
	v_exp_f32_e32 v24, v24
	s_nop 0
	v_add_f32_e32 v24, 1.0, v24
	v_rcp_f32_e32 v71, v24
	s_nop 0
	v_pk_mul_f32 v[68:69], v[68:69], v[70:71]
	v_lshlrev_b32_e32 v70, 16, v25
	v_and_b32_e32 v71, 0xffff0000, v25
	v_pk_mul_f32 v[24:25], v[34:35], v[54:55]
	v_pk_mul_f32 v[68:69], v[68:69], s[14:15] op_sel_hi:[1,0]
	v_pk_fma_f32 v[24:25], v[30:31], v[62:63], v[24:25]
	v_pk_mul_f32 v[62:63], v[42:43], v[70:71]
	s_nop 0
	v_pk_fma_f32 v[62:63], v[38:39], v[64:65], v[62:63]
	s_nop 0
	v_pk_add_f32 v[24:25], v[24:25], v[62:63]
	s_nop 0
	v_mul_f32_e32 v62, 0xbfb8aa3b, v24
	v_mul_f32_e32 v63, 0xbfb8aa3b, v25
	v_exp_f32_e32 v62, v62
	v_exp_f32_e32 v63, v63
	v_add_f32_e32 v62, 1.0, v62
	v_add_f32_e32 v63, 1.0, v63
	v_rcp_f32_e32 v62, v62
	v_rcp_f32_e32 v63, v63
	s_nop 0
	v_pk_mul_f32 v[24:25], v[24:25], v[62:63]
	s_nop 0
	v_pk_mul_f32 v[62:63], v[24:25], s[14:15] op_sel_hi:[1,0]
	v_pk_mul_f32 v[24:25], v[12:13], v[52:53]
	v_pk_mul_f32 v[12:13], v[12:13], v[50:51]
	v_pk_fma_f32 v[24:25], v[8:9], v[60:61], v[24:25]
	v_pk_mul_f32 v[60:61], v[20:21], v[72:73]
	v_pk_fma_f32 v[8:9], v[8:9], v[52:53], v[12:13]
	v_pk_fma_f32 v[60:61], v[16:17], v[50:51], v[60:61]
	s_nop 0
	v_pk_add_f32 v[24:25], v[24:25], v[60:61]
	s_nop 0
	v_mul_f32_e32 v26, 0xbfb8aa3b, v24
	v_exp_f32_e32 v26, v26
	s_nop 0
	v_add_f32_e32 v26, 1.0, v26
	v_rcp_f32_e32 v60, v26
	v_mul_f32_e32 v26, 0xbfb8aa3b, v25
	v_exp_f32_e32 v26, v26
	s_nop 0
	v_add_f32_e32 v26, 1.0, v26
	v_rcp_f32_e32 v61, v26
	v_pk_mul_f32 v[26:27], v[22:23], v[74:75]
	v_pk_mul_f32 v[24:25], v[24:25], v[60:61]
	s_nop 0
	v_pk_mul_f32 v[60:61], v[24:25], s[14:15] op_sel_hi:[1,0]
	v_pk_mul_f32 v[24:25], v[14:15], v[48:49]
	v_pk_fma_f32 v[26:27], v[18:19], v[44:45], v[26:27]
	v_pk_fma_f32 v[24:25], v[10:11], v[58:59], v[24:25]
	s_nop 0
	v_pk_add_f32 v[24:25], v[24:25], v[26:27]
	s_nop 0
	v_mul_f32_e32 v26, 0xbfb8aa3b, v24
	v_mul_f32_e32 v27, 0xbfb8aa3b, v25
	v_exp_f32_e32 v26, v26
	v_exp_f32_e32 v27, v27
	v_add_f32_e32 v26, 1.0, v26
	v_add_f32_e32 v27, 1.0, v27
	v_rcp_f32_e32 v26, v26
	v_rcp_f32_e32 v27, v27
	s_nop 0
	v_pk_mul_f32 v[24:25], v[24:25], v[26:27]
	s_nop 0
	v_pk_mul_f32 v[58:59], v[24:25], s[14:15] op_sel_hi:[1,0]
	v_cvt_pk_bf16_f32 v24, v68, v69
	v_cvt_pk_bf16_f32 v25, v62, v63
	v_cvt_pk_bf16_f32 v26, v60, v61
	v_cvt_pk_bf16_f32 v27, v58, v59
	ds_write_b128 v105, v[24:27] offset:3264
	v_lshlrev_b32_e32 v24, 16, v4
	v_and_b32_e32 v25, 0xffff0000, v4
	v_pk_mul_f32 v[26:27], v[32:33], v[66:67]
	v_pk_mul_f32 v[24:25], v[40:41], v[24:25]
	v_pk_fma_f32 v[26:27], v[28:29], v[56:57], v[26:27]
	v_pk_fma_f32 v[24:25], v[36:37], v[46:47], v[24:25]
	s_nop 0
	v_pk_add_f32 v[24:25], v[26:27], v[24:25]
	s_nop 0
	v_mul_f32_e32 v4, 0xbfb8aa3b, v24
	v_exp_f32_e32 v4, v4
	s_nop 0
	v_add_f32_e32 v4, 1.0, v4
	v_rcp_f32_e32 v26, v4
	v_mul_f32_e32 v4, 0xbfb8aa3b, v25
	v_exp_f32_e32 v4, v4
	s_nop 0
	v_add_f32_e32 v4, 1.0, v4
	v_rcp_f32_e32 v27, v4
	v_lshlrev_b32_e32 v4, 16, v5
	v_and_b32_e32 v5, 0xffff0000, v5
	v_pk_mul_f32 v[4:5], v[42:43], v[4:5]
	v_pk_mul_f32 v[24:25], v[24:25], v[26:27]
	v_pk_mul_f32 v[26:27], v[34:35], v[64:65]
	v_pk_fma_f32 v[4:5], v[38:39], v[70:71], v[4:5]
	v_pk_fma_f32 v[26:27], v[30:31], v[54:55], v[26:27]
	v_pk_mul_f32 v[24:25], v[24:25], s[14:15] op_sel_hi:[1,0]
	v_pk_add_f32 v[4:5], v[26:27], v[4:5]
	s_nop 0
	v_mul_f32_e32 v26, 0xbfb8aa3b, v4
	v_mul_f32_e32 v27, 0xbfb8aa3b, v5
	v_exp_f32_e32 v26, v26
	v_exp_f32_e32 v27, v27
	v_add_f32_e32 v26, 1.0, v26
	v_add_f32_e32 v27, 1.0, v27
	v_rcp_f32_e32 v26, v26
	v_rcp_f32_e32 v27, v27
	s_nop 0
	v_pk_mul_f32 v[4:5], v[4:5], v[26:27]
	s_nop 0
	v_pk_mul_f32 v[26:27], v[4:5], s[14:15] op_sel_hi:[1,0]
	v_lshlrev_b32_e32 v4, 16, v6
	v_and_b32_e32 v5, 0xffff0000, v6
	v_pk_mul_f32 v[4:5], v[20:21], v[4:5]
	s_nop 0
	v_pk_fma_f32 v[4:5], v[16:17], v[72:73], v[4:5]
	s_nop 0
	v_pk_add_f32 v[4:5], v[8:9], v[4:5]
	s_nop 0
	v_mul_f32_e32 v6, 0xbfb8aa3b, v4
	v_exp_f32_e32 v6, v6
	s_nop 0
	v_add_f32_e32 v6, 1.0, v6
	v_rcp_f32_e32 v8, v6
	v_mul_f32_e32 v6, 0xbfb8aa3b, v5
	v_exp_f32_e32 v6, v6
	s_nop 0
	v_add_f32_e32 v6, 1.0, v6
	v_rcp_f32_e32 v9, v6
	s_nop 0
	v_pk_mul_f32 v[4:5], v[4:5], v[8:9]
	s_nop 0
	v_pk_mul_f32 v[8:9], v[4:5], s[14:15] op_sel_hi:[1,0]
	v_lshlrev_b32_e32 v4, 16, v7
	v_and_b32_e32 v5, 0xffff0000, v7
	v_pk_mul_f32 v[6:7], v[14:15], v[44:45]
	v_pk_mul_f32 v[4:5], v[22:23], v[4:5]
	v_pk_fma_f32 v[6:7], v[10:11], v[48:49], v[6:7]
	v_pk_fma_f32 v[4:5], v[18:19], v[74:75], v[4:5]
	s_nop 0
	v_pk_add_f32 v[4:5], v[6:7], v[4:5]
	s_nop 0
	v_mul_f32_e32 v6, 0xbfb8aa3b, v4
	v_mul_f32_e32 v7, 0xbfb8aa3b, v5
	v_exp_f32_e32 v6, v6
	v_exp_f32_e32 v7, v7
	v_add_f32_e32 v6, 1.0, v6
	v_add_f32_e32 v7, 1.0, v7
	v_rcp_f32_e32 v6, v6
	v_rcp_f32_e32 v7, v7
	s_nop 0
	v_pk_mul_f32 v[4:5], v[4:5], v[6:7]
	s_nop 0
	v_pk_mul_f32 v[10:11], v[4:5], s[14:15] op_sel_hi:[1,0]
	v_cvt_pk_bf16_f32 v4, v24, v25
	v_cvt_pk_bf16_f32 v5, v26, v27
	v_cvt_pk_bf16_f32 v6, v8, v9
	v_cvt_pk_bf16_f32 v7, v10, v11
	v_add_u32_e32 v8, v103, v106
	ds_write_b128 v8, v[4:7]
	v_lshlrev_b32_e32 v4, 1, v3
	v_mov_b32_e32 v5, v1
	v_lshl_add_u64 v[6:7], s[0:1], 0, v[4:5]
	v_mov_b32_e32 v3, 0
	v_mov_b32_e32 v4, 0
	v_mov_b32_e32 v5, 0
	s_waitcnt vmcnt(0)
	s_and_saveexec_b64 s[0:1], vcc
	s_cbranch_execz .LBB0_182
; __device__ __forceinline__ float fsigmoid(float x) { return __builtin_amdgcn_rcpf(1.0f + __expf(-x)); }
; #define LAS __attribute__((address_space(3)))
; __device__ __forceinline__ void load_conv(LAS char* dst, const bf16_t* src, int pos0, const float* cw  , const LAS float* rowscale, float cscale, int tid) {
;     ...
;     for (int j = 0; j < 11; ++j) { const int rr = r0 - 3 + j;
;         if (j >= 3 || pos0 + rr >= 0) rw[j] = *(const u32x4*)(src + (ptrdiff_t)rr * PP + cg * 8); else rw[j] = (u32x4){0u, 0u, 0u, 0u}; }
;     float w[4][8];
; #pragma unroll
;     for (int j = 0; j < 4; ++j) { const f32x4 a = *(const f32x4*)(cw + j * 2048 + cg * 8), b = *(const f32x4*)(cw + j * 2048 + cg * 8 + 4);
;         w[j][0] = a.x; w[j][1] = a.y; w[j][2] = a.z; w[j][3] = a.w; w[j][4] = b.x; w[j][5] = b.y; w[j][6] = b.z; w[j][7] = b.w; }
;     float sc8[8];
; #pragma unroll
;     for (int r = 0; r < 8; ++r) sc8[r] = rowscale ? rowscale[r0 + r] : cscale;
;     float u[3][8];
; #pragma unroll
;     for (int j = 0; j < 3; ++j) unpack8(rw[j], u[j]);
; #pragma unroll
;     for (int r = 0; r < 8; ++r) {
;         float x[8]; unpack8(rw[3 + r], x);
;         const float sc = sc8[r];
;         float o[8];
; #pragma unroll
;         for (int e = 0; e < 8; ++e) { const float cv = (w[0][e] * u[0][e] + w[1][e] * u[1][e]) + (w[2][e] * u[2][e] + w[3][e] * x[e]); o[e] = cv * fsigmoid(cv) * sc;
;             u[0][e] = u[1][e]; u[1][e] = u[2][e]; u[2][e] = x[e]; }
;         *(LAS u32x4*)(dst + (r0 + r) * PIT + cg * 16) = pack8(o);
	v_lshlrev_b64 v[2:3], 11, v[80:81]
	v_lshl_add_u64 v[2:3], v[6:7], 0, v[2:3]
	v_mov_b64_e32 v[2:3], v[132:133]
	v_mov_b64_e32 v[4:5], v[134:135]
.LBB0_182:
	s_or_b64 exec, exec, s[0:1]
	v_mov_b32_e32 v66, 0
	v_mov_b32_e32 v70, 0
	v_mov_b32_e32 v71, 0
	v_mov_b32_e32 v72, 0
	v_mov_b32_e32 v73, 0
	s_and_saveexec_b64 s[0:1], s[4:5]
	s_cbranch_execz .LBB0_184
	v_lshlrev_b64 v[8:9], 11, v[82:83]
	v_lshl_add_u64 v[8:9], v[6:7], 0, v[8:9]
	v_mov_b64_e32 v[70:71], v[136:137]
	v_mov_b64_e32 v[72:73], v[138:139]
.LBB0_184:
	s_or_b64 exec, exec, s[0:1]
	v_mov_b32_e32 v67, 0
	v_mov_b32_e32 v68, 0
	v_mov_b32_e32 v69, 0
	s_and_saveexec_b64 s[0:1], s[6:7]
	s_cbranch_execz .LBB0_186
	v_lshlrev_b64 v[8:9], 11, v[84:85]
	v_lshl_add_u64 v[8:9], v[6:7], 0, v[8:9]
	v_mov_b64_e32 v[66:67], v[140:141]
	v_mov_b64_e32 v[68:69], v[142:143]
.LBB0_186:
	s_or_b64 exec, exec, s[0:1]
	v_lshl_add_u64 v[8:9], v[6:7], 0, v[86:87]
	v_readlane_b32 s0, v255, 19
	v_mov_b64_e32 v[74:75], v[144:145]
	v_mov_b64_e32 v[76:77], v[146:147]
	v_lshl_add_u64 v[8:9], v[6:7], 0, v[88:89]
	s_add_u32 s0, s0, s11
	v_readlane_b32 s1, v255, 21
	v_mov_b64_e32 v[62:63], v[148:149]
	v_mov_b64_e32 v[64:65], v[150:151]
	v_lshl_add_u64 v[8:9], v[6:7], 0, v[90:91]
	s_addc_u32 s1, s1, 0
	v_mov_b64_e32 v[58:59], v[152:153]
	v_mov_b64_e32 v[60:61], v[154:155]
	v_lshl_add_u64 v[8:9], v[6:7], 0, v[92:93]
	v_mov_b32_e32 v103, v1
	v_mov_b64_e32 v[54:55], v[156:157]
	v_mov_b64_e32 v[56:57], v[158:159]
	v_lshl_add_u64 v[8:9], v[6:7], 0, v[94:95]
	v_lshl_add_u64 v[22:23], s[0:1], 0, v[102:103]
	v_mov_b64_e32 v[50:51], v[160:161]
	v_mov_b64_e32 v[52:53], v[162:163]
	v_lshl_add_u64 v[8:9], v[6:7], 0, v[96:97]
	v_add_co_u32_e32 v16, vcc, s97, v22
	v_mov_b64_e32 v[46:47], v[164:165]
	v_mov_b64_e32 v[48:49], v[166:167]
	v_lshl_add_u64 v[8:9], v[6:7], 0, v[98:99]
	v_lshl_add_u64 v[6:7], v[6:7], 0, v[100:101]
	v_addc_co_u32_e32 v17, vcc, 0, v23, vcc
	v_mov_b64_e32 v[38:39], v[168:169]
	v_mov_b64_e32 v[40:41], v[170:171]
	s_mov_b64 s[4:5], 0x4000
	v_mov_b64_e32 v[6:7], v[172:173]
	v_mov_b64_e32 v[8:9], v[174:175]
	s_nop 0
	v_mov_b64_e32 v[10:11], v[176:177]
	v_mov_b64_e32 v[12:13], v[178:179]
	v_mov_b64_e32 v[26:27], v[180:181]
	v_mov_b64_e32 v[28:29], v[182:183]
	s_mov_b64 s[0:1], 0x2000
	v_add_co_u32_e32 v20, vcc, s53, v22
	v_lshl_add_u64 v[14:15], v[22:23], 0, s[0:1]
	v_lshl_add_u64 v[18:19], v[22:23], 0, s[4:5]
	v_addc_co_u32_e32 v21, vcc, 0, v23, vcc
	s_mov_b64 s[4:5], 0x6000
	s_movk_i32 s1, 0x6000
	v_lshl_add_u64 v[24:25], v[22:23], 0, s[4:5]
	v_add_co_u32_e32 v22, vcc, s1, v22
	v_mov_b64_e32 v[30:31], v[184:185]
	v_mov_b64_e32 v[32:33], v[186:187]
	s_nop 0
	v_mov_b64_e32 v[14:15], v[188:189]
	v_mov_b64_e32 v[16:17], v[190:191]
	v_addc_co_u32_e32 v23, vcc, 0, v23, vcc
	v_mov_b64_e32 v[34:35], v[206:207]
	v_mov_b64_e32 v[36:37], v[208:209]
	s_nop 0
	v_mov_b64_e32 v[18:19], v[210:211]
	v_mov_b64_e32 v[20:21], v[212:213]
	s_nop 0
	v_mov_b64_e32 v[42:43], v[214:215]
	v_mov_b64_e32 v[44:45], v[216:217]
	s_nop 0
	v_mov_b64_e32 v[22:23], v[218:219]
	v_mov_b64_e32 v[24:25], v[220:221]
	s_waitcnt vmcnt(16)
	v_lshlrev_b32_e32 v82, 16, v70
	v_and_b32_e32 v83, 0xffff0000, v70
	v_lshlrev_b32_e32 v84, 16, v2
	v_and_b32_e32 v85, 0xffff0000, v2
	v_lshlrev_b32_e32 v80, 16, v66
	v_and_b32_e32 v81, 0xffff0000, v66
	v_lshlrev_b32_e32 v90, 16, v71
	v_and_b32_e32 v91, 0xffff0000, v71
	v_lshlrev_b32_e32 v70, 16, v67
	v_and_b32_e32 v71, 0xffff0000, v67
	v_lshlrev_b32_e32 v92, 16, v4
	v_and_b32_e32 v93, 0xffff0000, v4
	v_lshlrev_b32_e32 v88, 16, v68
	v_and_b32_e32 v89, 0xffff0000, v68
	v_lshlrev_b32_e32 v96, 16, v5
	v_and_b32_e32 v97, 0xffff0000, v5
	v_readlane_b32 s1, v254, 36
	s_ashr_i32 s73, s72, 31
	s_ashr_i32 s75, s10, 6
	v_add_u32_e32 v0, s1, v0
	s_lshl_b64 s[4:5], s[72:73], 17
	v_readlane_b32 s6, v252, 0
	v_readlane_b32 s7, v252, 1
	s_add_u32 s60, s6, s4
	s_addc_u32 s61, s7, s5
	s_mul_i32 s1, s75, 0x2200
	v_and_b32_e32 v105, 15, v104
	s_mov_b32 s0, 0
	s_waitcnt vmcnt(15)
	v_lshlrev_b32_e32 v78, 16, v74
	v_and_b32_e32 v79, 0xffff0000, v74
	v_and_b32_e32 v5, 0xffff0000, v77
	s_waitcnt vmcnt(5)
	v_pk_mul_f32 v[86:87], v[30:31], v[82:83]
	s_nop 0
	v_pk_fma_f32 v[84:85], v[26:27], v[84:85], v[86:87]
	v_pk_mul_f32 v[66:67], v[32:33], v[90:91]
	s_waitcnt vmcnt(1)
	v_pk_mul_f32 v[86:87], v[42:43], v[78:79]
	s_nop 0
	v_pk_fma_f32 v[86:87], v[34:35], v[80:81], v[86:87]
	s_nop 0
	v_pk_add_f32 v[84:85], v[84:85], v[86:87]
	s_nop 0
	v_mul_f32_e32 v2, 0xbfb8aa3b, v84
	v_exp_f32_e32 v2, v2
	s_nop 0
	v_add_f32_e32 v2, 1.0, v2
	v_rcp_f32_e32 v86, v2
	v_mul_f32_e32 v2, 0xbfb8aa3b, v85
	v_exp_f32_e32 v2, v2
	s_nop 0
	v_add_f32_e32 v2, 1.0, v2
	v_rcp_f32_e32 v87, v2
	v_lshlrev_b32_e32 v2, 16, v75
	v_pk_mul_f32 v[84:85], v[84:85], v[86:87]
	v_lshlrev_b32_e32 v86, 16, v3
	v_and_b32_e32 v87, 0xffff0000, v3
	v_and_b32_e32 v3, 0xffff0000, v75
	v_pk_mul_f32 v[74:75], v[44:45], v[2:3]
	v_pk_fma_f32 v[66:67], v[28:29], v[86:87], v[66:67]
	v_pk_fma_f32 v[74:75], v[36:37], v[70:71], v[74:75]
	v_cvt_pk_bf16_f32 v84, v84, v85
	v_pk_add_f32 v[66:67], v[66:67], v[74:75]
	s_nop 0
	v_mul_f32_e32 v74, 0xbfb8aa3b, v66
	v_mul_f32_e32 v75, 0xbfb8aa3b, v67
	v_exp_f32_e32 v74, v74
	v_exp_f32_e32 v75, v75
	v_add_f32_e32 v74, 1.0, v74
	v_add_f32_e32 v75, 1.0, v75
	v_rcp_f32_e32 v74, v74
	v_rcp_f32_e32 v75, v75
	s_nop 0
	v_pk_mul_f32 v[86:87], v[66:67], v[74:75]
	v_lshlrev_b32_e32 v74, 16, v72
	v_and_b32_e32 v75, 0xffff0000, v72
	v_lshlrev_b32_e32 v66, 16, v76
	v_and_b32_e32 v67, 0xffff0000, v76
	v_pk_mul_f32 v[94:95], v[14:15], v[74:75]
	v_lshlrev_b32_e32 v72, 16, v73
	v_pk_fma_f32 v[92:93], v[10:11], v[92:93], v[94:95]
	s_waitcnt vmcnt(0)
; __device__ __forceinline__ float fsigmoid(float x) { return __builtin_amdgcn_rcpf(1.0f + __expf(-x)); }
; #define LAS __attribute__((address_space(3)))
; __device__ __forceinline__ void load_conv(LAS char* dst, const bf16_t* src, int pos0, const float* cw  , const LAS float* rowscale, float cscale, int tid) {
;     ...
;     for (int r = 0; r < 8; ++r) {
;         float x[8]; unpack8(rw[3 + r], x);
;         const float sc = sc8[r];
;         float o[8];
; #pragma unroll
;         for (int e = 0; e < 8; ++e) { const float cv = (w[0][e] * u[0][e] + w[1][e] * u[1][e]) + (w[2][e] * u[2][e] + w[3][e] * x[e]); o[e] = cv * fsigmoid(cv) * sc;
;             u[0][e] = u[1][e]; u[1][e] = u[2][e]; u[2][e] = x[e]; }
;         *(LAS u32x4*)(dst + (r0 + r) * PIT + cg * 16) = pack8(o);
	v_pk_mul_f32 v[94:95], v[22:23], v[66:67]
	v_and_b32_e32 v73, 0xffff0000, v73
	v_pk_fma_f32 v[94:95], v[18:19], v[88:89], v[94:95]
	v_cvt_pk_bf16_f32 v85, v86, v87
	v_pk_add_f32 v[92:93], v[92:93], v[94:95]
	s_nop 0
	v_mul_f32_e32 v4, 0xbfb8aa3b, v92
	v_exp_f32_e32 v4, v4
	s_nop 0
	v_add_f32_e32 v4, 1.0, v4
	v_rcp_f32_e32 v94, v4
	v_mul_f32_e32 v4, 0xbfb8aa3b, v93
	v_exp_f32_e32 v4, v4
	s_nop 0
	v_add_f32_e32 v4, 1.0, v4
	v_rcp_f32_e32 v95, v4
	v_lshlrev_b32_e32 v4, 16, v77
	v_pk_mul_f32 v[76:77], v[24:25], v[4:5]
	v_pk_mul_f32 v[94:95], v[92:93], v[94:95]
	v_lshlrev_b32_e32 v92, 16, v69
	v_and_b32_e32 v93, 0xffff0000, v69
	v_pk_mul_f32 v[68:69], v[16:17], v[72:73]
	v_pk_fma_f32 v[76:77], v[20:21], v[92:93], v[76:77]
	v_pk_fma_f32 v[68:69], v[12:13], v[96:97], v[68:69]
	v_cvt_pk_bf16_f32 v86, v94, v95
	v_pk_add_f32 v[68:69], v[68:69], v[76:77]
	v_add_u32_e32 v94, v0, v107
	v_mul_f32_e32 v76, 0xbfb8aa3b, v68
	v_mul_f32_e32 v77, 0xbfb8aa3b, v69
	v_exp_f32_e32 v76, v76
	v_exp_f32_e32 v77, v77
	v_add_u32_e32 v0, v0, v106
	v_add_f32_e32 v76, 1.0, v76
	v_add_f32_e32 v77, 1.0, v77
	v_rcp_f32_e32 v76, v76
	v_rcp_f32_e32 v77, v77
	s_nop 0
	v_pk_mul_f32 v[68:69], v[68:69], v[76:77]
	s_nop 0
	v_cvt_pk_bf16_f32 v87, v68, v69
	ds_write_b128 v94, v[84:87]
	v_lshlrev_b32_e32 v86, 16, v62
	v_and_b32_e32 v87, 0xffff0000, v62
	v_pk_mul_f32 v[68:69], v[30:31], v[80:81]
	v_pk_mul_f32 v[76:77], v[42:43], v[86:87]
	v_pk_fma_f32 v[68:69], v[26:27], v[82:83], v[68:69]
	v_pk_fma_f32 v[76:77], v[34:35], v[78:79], v[76:77]
	v_lshlrev_b32_e32 v84, 16, v63
	v_pk_add_f32 v[68:69], v[68:69], v[76:77]
	v_and_b32_e32 v85, 0xffff0000, v63
	v_mul_f32_e32 v62, 0xbfb8aa3b, v68
	v_exp_f32_e32 v62, v62
	v_lshlrev_b32_e32 v82, 16, v64
	v_and_b32_e32 v83, 0xffff0000, v64
	v_add_f32_e32 v62, 1.0, v62
	v_rcp_f32_e32 v76, v62
	v_mul_f32_e32 v62, 0xbfb8aa3b, v69
	v_exp_f32_e32 v62, v62
	s_nop 0
	v_add_f32_e32 v62, 1.0, v62
	v_rcp_f32_e32 v77, v62
	v_pk_mul_f32 v[62:63], v[32:33], v[70:71]
	v_pk_mul_f32 v[68:69], v[68:69], v[76:77]
	v_pk_mul_f32 v[76:77], v[44:45], v[84:85]
	v_pk_fma_f32 v[62:63], v[28:29], v[90:91], v[62:63]
	v_pk_fma_f32 v[76:77], v[36:37], v[2:3], v[76:77]
	s_nop 0
	v_pk_add_f32 v[62:63], v[62:63], v[76:77]
	s_nop 0
	v_mul_f32_e32 v76, 0xbfb8aa3b, v62
	v_mul_f32_e32 v77, 0xbfb8aa3b, v63
	v_exp_f32_e32 v76, v76
	v_exp_f32_e32 v77, v77
	v_add_f32_e32 v76, 1.0, v76
	v_add_f32_e32 v77, 1.0, v77
	v_rcp_f32_e32 v76, v76
	v_rcp_f32_e32 v77, v77
	s_nop 0
	v_pk_mul_f32 v[90:91], v[62:63], v[76:77]
	v_pk_mul_f32 v[62:63], v[14:15], v[88:89]
	v_lshlrev_b32_e32 v76, 16, v65
	v_pk_fma_f32 v[62:63], v[10:11], v[74:75], v[62:63]
	v_pk_mul_f32 v[74:75], v[22:23], v[82:83]
	v_and_b32_e32 v77, 0xffff0000, v65
	v_pk_fma_f32 v[74:75], v[18:19], v[66:67], v[74:75]
	s_nop 0
	v_pk_add_f32 v[62:63], v[62:63], v[74:75]
	s_nop 0
	v_mul_f32_e32 v64, 0xbfb8aa3b, v62
	v_exp_f32_e32 v64, v64
	s_nop 0
	v_add_f32_e32 v64, 1.0, v64
	v_rcp_f32_e32 v74, v64
	v_mul_f32_e32 v64, 0xbfb8aa3b, v63
	v_exp_f32_e32 v64, v64
	s_nop 0
	v_add_f32_e32 v64, 1.0, v64
	v_rcp_f32_e32 v75, v64
	v_pk_mul_f32 v[64:65], v[24:25], v[76:77]
	v_pk_mul_f32 v[74:75], v[62:63], v[74:75]
	v_pk_mul_f32 v[62:63], v[16:17], v[92:93]
	v_pk_fma_f32 v[64:65], v[20:21], v[4:5], v[64:65]
	v_pk_fma_f32 v[62:63], v[12:13], v[72:73], v[62:63]
	s_nop 0
	v_pk_add_f32 v[62:63], v[62:63], v[64:65]
	s_nop 0
	v_mul_f32_e32 v64, 0xbfb8aa3b, v62
	v_mul_f32_e32 v65, 0xbfb8aa3b, v63
	v_exp_f32_e32 v64, v64
	v_exp_f32_e32 v65, v65
	v_add_f32_e32 v64, 1.0, v64
	v_add_f32_e32 v65, 1.0, v65
	v_rcp_f32_e32 v64, v64
	v_rcp_f32_e32 v65, v65
	s_nop 0
	v_pk_mul_f32 v[72:73], v[62:63], v[64:65]
	v_cvt_pk_bf16_f32 v62, v68, v69
	v_cvt_pk_bf16_f32 v63, v90, v91
	v_cvt_pk_bf16_f32 v64, v74, v75
	v_cvt_pk_bf16_f32 v65, v72, v73
	v_lshlrev_b32_e32 v74, 16, v58
	v_and_b32_e32 v75, 0xffff0000, v58
	ds_write_b128 v94, v[62:65] offset:544
	v_pk_mul_f32 v[62:63], v[30:31], v[78:79]
	v_pk_mul_f32 v[64:65], v[42:43], v[74:75]
	v_pk_fma_f32 v[62:63], v[26:27], v[80:81], v[62:63]
	v_pk_fma_f32 v[64:65], v[34:35], v[86:87], v[64:65]
	v_lshlrev_b32_e32 v72, 16, v59
	v_pk_add_f32 v[62:63], v[62:63], v[64:65]
	v_and_b32_e32 v73, 0xffff0000, v59
	v_mul_f32_e32 v58, 0xbfb8aa3b, v62
	v_exp_f32_e32 v58, v58
	v_lshlrev_b32_e32 v68, 16, v60
	v_and_b32_e32 v69, 0xffff0000, v60
	v_add_f32_e32 v58, 1.0, v58
	v_rcp_f32_e32 v64, v58
	v_mul_f32_e32 v58, 0xbfb8aa3b, v63
	v_exp_f32_e32 v58, v58
	s_nop 0
	v_add_f32_e32 v58, 1.0, v58
	v_rcp_f32_e32 v65, v58
	v_pk_mul_f32 v[58:59], v[32:33], v[2:3]
	v_pk_mul_f32 v[62:63], v[62:63], v[64:65]
	v_pk_mul_f32 v[64:65], v[44:45], v[72:73]
	v_pk_fma_f32 v[58:59], v[28:29], v[70:71], v[58:59]
	v_pk_fma_f32 v[64:65], v[36:37], v[84:85], v[64:65]
	s_nop 0
	v_pk_add_f32 v[58:59], v[58:59], v[64:65]
	s_nop 0
	v_mul_f32_e32 v64, 0xbfb8aa3b, v58
	v_mul_f32_e32 v65, 0xbfb8aa3b, v59
	v_exp_f32_e32 v64, v64
	v_exp_f32_e32 v65, v65
	v_add_f32_e32 v64, 1.0, v64
	v_add_f32_e32 v65, 1.0, v65
	v_rcp_f32_e32 v64, v64
	v_rcp_f32_e32 v65, v65
	s_nop 0
	v_pk_mul_f32 v[70:71], v[58:59], v[64:65]
	v_pk_mul_f32 v[58:59], v[14:15], v[66:67]
	v_pk_mul_f32 v[64:65], v[22:23], v[68:69]
	v_pk_fma_f32 v[58:59], v[10:11], v[88:89], v[58:59]
	v_pk_fma_f32 v[64:65], v[18:19], v[82:83], v[64:65]
	s_nop 0
	v_pk_add_f32 v[58:59], v[58:59], v[64:65]
	s_nop 0
	v_mul_f32_e32 v60, 0xbfb8aa3b, v58
	v_exp_f32_e32 v60, v60
	s_nop 0
	v_add_f32_e32 v60, 1.0, v60
	v_rcp_f32_e32 v64, v60
	v_mul_f32_e32 v60, 0xbfb8aa3b, v59
	v_exp_f32_e32 v60, v60
	s_nop 0
	v_add_f32_e32 v60, 1.0, v60
	v_rcp_f32_e32 v65, v60
	s_nop 0
	v_pk_mul_f32 v[80:81], v[58:59], v[64:65]
	v_lshlrev_b32_e32 v64, 16, v61
; __device__ __forceinline__ float fsigmoid(float x) { return __builtin_amdgcn_rcpf(1.0f + __expf(-x)); }
; #define LAS __attribute__((address_space(3)))
; __device__ __forceinline__ void load_conv(LAS char* dst, const bf16_t* src, int pos0, const float* cw  , const LAS float* rowscale, float cscale, int tid) {
;     ...
;     for (int r = 0; r < 8; ++r) {
;         float x[8]; unpack8(rw[3 + r], x);
;         const float sc = sc8[r];
;         float o[8];
; #pragma unroll
;         for (int e = 0; e < 8; ++e) { const float cv = (w[0][e] * u[0][e] + w[1][e] * u[1][e]) + (w[2][e] * u[2][e] + w[3][e] * x[e]); o[e] = cv * fsigmoid(cv) * sc;
;             u[0][e] = u[1][e]; u[1][e] = u[2][e]; u[2][e] = x[e]; }
;         *(LAS u32x4*)(dst + (r0 + r) * PIT + cg * 16) = pack8(o);
	v_and_b32_e32 v65, 0xffff0000, v61
	v_pk_mul_f32 v[58:59], v[16:17], v[4:5]
	v_pk_mul_f32 v[60:61], v[24:25], v[64:65]
	v_pk_fma_f32 v[58:59], v[12:13], v[92:93], v[58:59]
	v_pk_fma_f32 v[60:61], v[20:21], v[76:77], v[60:61]
	s_nop 0
	v_pk_add_f32 v[58:59], v[58:59], v[60:61]
	s_nop 0
	v_mul_f32_e32 v60, 0xbfb8aa3b, v58
	v_mul_f32_e32 v61, 0xbfb8aa3b, v59
	v_exp_f32_e32 v60, v60
	v_exp_f32_e32 v61, v61
	v_add_f32_e32 v60, 1.0, v60
	v_add_f32_e32 v61, 1.0, v61
	v_rcp_f32_e32 v60, v60
	v_rcp_f32_e32 v61, v61
	s_nop 0
	v_pk_mul_f32 v[88:89], v[58:59], v[60:61]
	v_cvt_pk_bf16_f32 v58, v62, v63
	v_cvt_pk_bf16_f32 v59, v70, v71
	v_cvt_pk_bf16_f32 v60, v80, v81
	v_cvt_pk_bf16_f32 v61, v88, v89
	v_lshlrev_b32_e32 v62, 16, v54
	v_and_b32_e32 v63, 0xffff0000, v54
	ds_write_b128 v94, v[58:61] offset:1088
	v_pk_mul_f32 v[58:59], v[30:31], v[86:87]
	v_pk_mul_f32 v[60:61], v[42:43], v[62:63]
	v_pk_fma_f32 v[58:59], v[26:27], v[78:79], v[58:59]
	v_pk_fma_f32 v[60:61], v[34:35], v[74:75], v[60:61]
	s_nop 0
	v_pk_add_f32 v[58:59], v[58:59], v[60:61]
	s_nop 0
	v_mul_f32_e32 v54, 0xbfb8aa3b, v58
	v_exp_f32_e32 v54, v54
	s_nop 0
	v_add_f32_e32 v54, 1.0, v54
	v_rcp_f32_e32 v60, v54
	v_mul_f32_e32 v54, 0xbfb8aa3b, v59
	v_exp_f32_e32 v54, v54
	s_nop 0
	v_add_f32_e32 v54, 1.0, v54
	v_rcp_f32_e32 v61, v54
	s_nop 0
	v_pk_mul_f32 v[70:71], v[58:59], v[60:61]
	v_lshlrev_b32_e32 v60, 16, v55
	v_and_b32_e32 v61, 0xffff0000, v55
	v_pk_mul_f32 v[54:55], v[32:33], v[84:85]
	v_lshlrev_b32_e32 v58, 16, v56
	v_pk_fma_f32 v[2:3], v[28:29], v[2:3], v[54:55]
	v_pk_mul_f32 v[54:55], v[44:45], v[60:61]
	v_and_b32_e32 v59, 0xffff0000, v56
	v_pk_fma_f32 v[54:55], v[36:37], v[72:73], v[54:55]
	s_nop 0
	v_pk_add_f32 v[2:3], v[2:3], v[54:55]
	s_nop 0
	v_mul_f32_e32 v54, 0xbfb8aa3b, v2
	v_mul_f32_e32 v55, 0xbfb8aa3b, v3
	v_exp_f32_e32 v54, v54
	v_exp_f32_e32 v55, v55
	v_add_f32_e32 v54, 1.0, v54
	v_add_f32_e32 v55, 1.0, v55
	v_rcp_f32_e32 v54, v54
	v_rcp_f32_e32 v55, v55
	s_nop 0
	v_pk_mul_f32 v[54:55], v[2:3], v[54:55]
	v_pk_mul_f32 v[2:3], v[14:15], v[82:83]
	s_nop 0
	v_pk_fma_f32 v[2:3], v[10:11], v[66:67], v[2:3]
	v_pk_mul_f32 v[66:67], v[22:23], v[58:59]
	s_nop 0
	v_pk_fma_f32 v[66:67], v[18:19], v[68:69], v[66:67]
	s_nop 0
	v_pk_add_f32 v[2:3], v[2:3], v[66:67]
	s_nop 0
	v_mul_f32_e32 v56, 0xbfb8aa3b, v2
	v_exp_f32_e32 v56, v56
	s_nop 0
	v_add_f32_e32 v56, 1.0, v56
	v_rcp_f32_e32 v66, v56
	v_mul_f32_e32 v56, 0xbfb8aa3b, v3
	v_exp_f32_e32 v56, v56
	s_nop 0
	v_add_f32_e32 v56, 1.0, v56
	v_rcp_f32_e32 v67, v56
	v_lshlrev_b32_e32 v56, 16, v57
	v_and_b32_e32 v57, 0xffff0000, v57
	v_pk_mul_f32 v[66:67], v[2:3], v[66:67]
	v_pk_mul_f32 v[2:3], v[16:17], v[76:77]
	s_nop 0
	v_pk_fma_f32 v[2:3], v[12:13], v[4:5], v[2:3]
	v_pk_mul_f32 v[4:5], v[24:25], v[56:57]
	s_nop 0
	v_pk_fma_f32 v[4:5], v[20:21], v[64:65], v[4:5]
	s_nop 0
	v_pk_add_f32 v[2:3], v[2:3], v[4:5]
	s_nop 0
	v_mul_f32_e32 v4, 0xbfb8aa3b, v2
	v_mul_f32_e32 v5, 0xbfb8aa3b, v3
	v_exp_f32_e32 v4, v4
	v_exp_f32_e32 v5, v5
	v_add_f32_e32 v4, 1.0, v4
	v_add_f32_e32 v5, 1.0, v5
	v_rcp_f32_e32 v4, v4
	v_rcp_f32_e32 v5, v5
	s_nop 0
	v_pk_mul_f32 v[78:79], v[2:3], v[4:5]
	v_cvt_pk_bf16_f32 v2, v70, v71
	v_cvt_pk_bf16_f32 v3, v54, v55
	v_cvt_pk_bf16_f32 v4, v66, v67
	v_cvt_pk_bf16_f32 v5, v78, v79
	v_lshlrev_b32_e32 v54, 16, v50
	v_and_b32_e32 v55, 0xffff0000, v50
	ds_write_b128 v94, v[2:5] offset:1632
	v_pk_mul_f32 v[2:3], v[30:31], v[74:75]
	v_pk_mul_f32 v[4:5], v[42:43], v[54:55]
	v_pk_fma_f32 v[2:3], v[26:27], v[86:87], v[2:3]
	v_pk_fma_f32 v[4:5], v[34:35], v[62:63], v[4:5]
	v_lshlrev_b32_e32 v50, 16, v51
	v_pk_add_f32 v[2:3], v[2:3], v[4:5]
	v_and_b32_e32 v51, 0xffff0000, v51
	v_mul_f32_e32 v4, 0xbfb8aa3b, v2
	v_mul_f32_e32 v5, 0xbfb8aa3b, v3
	v_exp_f32_e32 v4, v4
	v_exp_f32_e32 v5, v5
	v_add_f32_e32 v4, 1.0, v4
	v_add_f32_e32 v5, 1.0, v5
	v_rcp_f32_e32 v4, v4
	v_rcp_f32_e32 v5, v5
	s_nop 0
	v_pk_mul_f32 v[66:67], v[2:3], v[4:5]
	v_pk_mul_f32 v[2:3], v[32:33], v[72:73]
	v_pk_mul_f32 v[4:5], v[44:45], v[50:51]
	v_pk_fma_f32 v[2:3], v[28:29], v[84:85], v[2:3]
	v_pk_fma_f32 v[4:5], v[36:37], v[60:61], v[4:5]
	s_nop 0
	v_pk_add_f32 v[2:3], v[2:3], v[4:5]
	s_nop 0
	v_mul_f32_e32 v4, 0xbfb8aa3b, v2
	v_mul_f32_e32 v5, 0xbfb8aa3b, v3
	v_exp_f32_e32 v4, v4
	v_exp_f32_e32 v5, v5
	v_add_f32_e32 v4, 1.0, v4
	v_add_f32_e32 v5, 1.0, v5
	v_rcp_f32_e32 v4, v4
	v_rcp_f32_e32 v5, v5
	s_nop 0
	v_pk_mul_f32 v[70:71], v[2:3], v[4:5]
	v_lshlrev_b32_e32 v4, 16, v52
	v_and_b32_e32 v5, 0xffff0000, v52
	v_pk_mul_f32 v[2:3], v[14:15], v[68:69]
	v_pk_mul_f32 v[78:79], v[22:23], v[4:5]
	v_pk_fma_f32 v[2:3], v[10:11], v[82:83], v[2:3]
	v_pk_fma_f32 v[78:79], v[18:19], v[58:59], v[78:79]
	s_nop 0
	v_pk_add_f32 v[2:3], v[2:3], v[78:79]
	s_nop 0
	v_mul_f32_e32 v52, 0xbfb8aa3b, v2
	v_exp_f32_e32 v52, v52
	s_nop 0
	v_add_f32_e32 v52, 1.0, v52
	v_rcp_f32_e32 v78, v52
	v_mul_f32_e32 v52, 0xbfb8aa3b, v3
	v_exp_f32_e32 v52, v52
	s_nop 0
	v_add_f32_e32 v52, 1.0, v52
	v_rcp_f32_e32 v79, v52
	s_nop 0
	v_pk_mul_f32 v[78:79], v[2:3], v[78:79]
	v_lshlrev_b32_e32 v2, 16, v53
	v_and_b32_e32 v3, 0xffff0000, v53
	v_pk_mul_f32 v[52:53], v[16:17], v[64:65]
	v_cvt_pk_bf16_f32 v78, v78, v79
	v_pk_fma_f32 v[52:53], v[12:13], v[76:77], v[52:53]
	v_pk_mul_f32 v[76:77], v[24:25], v[2:3]
	s_nop 0
	v_pk_fma_f32 v[76:77], v[20:21], v[56:57], v[76:77]
	s_nop 0
	v_pk_add_f32 v[52:53], v[52:53], v[76:77]
	s_nop 0
	v_mul_f32_e32 v76, 0xbfb8aa3b, v52
	v_mul_f32_e32 v77, 0xbfb8aa3b, v53
	v_exp_f32_e32 v76, v76
	v_exp_f32_e32 v77, v77
	v_add_f32_e32 v76, 1.0, v76
	v_add_f32_e32 v77, 1.0, v77
	v_rcp_f32_e32 v76, v76
	v_rcp_f32_e32 v77, v77
	s_nop 0
	v_pk_mul_f32 v[52:53], v[52:53], v[76:77]
; __device__ __forceinline__ float fsigmoid(float x) { return __builtin_amdgcn_rcpf(1.0f + __expf(-x)); }
; #define LAS __attribute__((address_space(3)))
; __device__ __forceinline__ void load_conv(LAS char* dst, const bf16_t* src, int pos0, const float* cw  , const LAS float* rowscale, float cscale, int tid) {
;     ...
;     for (int r = 0; r < 8; ++r) {
;         float x[8]; unpack8(rw[3 + r], x);
;         const float sc = sc8[r];
;         float o[8];
; #pragma unroll
;         for (int e = 0; e < 8; ++e) { const float cv = (w[0][e] * u[0][e] + w[1][e] * u[1][e]) + (w[2][e] * u[2][e] + w[3][e] * x[e]); o[e] = cv * fsigmoid(cv) * sc;
;             u[0][e] = u[1][e]; u[1][e] = u[2][e]; u[2][e] = x[e]; }
;         *(LAS u32x4*)(dst + (r0 + r) * PIT + cg * 16) = pack8(o);
	v_cvt_pk_bf16_f32 v77, v70, v71
	v_lshlrev_b32_e32 v70, 16, v46
	v_and_b32_e32 v71, 0xffff0000, v46
	v_cvt_pk_bf16_f32 v76, v66, v67
	v_cvt_pk_bf16_f32 v79, v52, v53
	v_pk_mul_f32 v[52:53], v[30:31], v[62:63]
	v_pk_mul_f32 v[66:67], v[42:43], v[70:71]
	v_pk_fma_f32 v[52:53], v[26:27], v[74:75], v[52:53]
	v_pk_fma_f32 v[66:67], v[34:35], v[54:55], v[66:67]
	ds_write_b128 v94, v[76:79] offset:2176
	v_pk_add_f32 v[52:53], v[52:53], v[66:67]
	s_nop 0
	v_mul_f32_e32 v46, 0xbfb8aa3b, v52
	v_exp_f32_e32 v46, v46
	s_nop 0
	v_add_f32_e32 v46, 1.0, v46
	v_rcp_f32_e32 v66, v46
	v_mul_f32_e32 v46, 0xbfb8aa3b, v53
	v_exp_f32_e32 v46, v46
	s_nop 0
	v_add_f32_e32 v46, 1.0, v46
	v_rcp_f32_e32 v67, v46
	s_nop 0
	v_pk_mul_f32 v[74:75], v[52:53], v[66:67]
	v_lshlrev_b32_e32 v66, 16, v47
	v_and_b32_e32 v67, 0xffff0000, v47
	v_pk_mul_f32 v[46:47], v[32:33], v[60:61]
	v_pk_mul_f32 v[52:53], v[44:45], v[66:67]
	v_pk_fma_f32 v[46:47], v[28:29], v[72:73], v[46:47]
	v_pk_fma_f32 v[52:53], v[36:37], v[50:51], v[52:53]
	v_cvt_pk_bf16_f32 v72, v74, v75
	v_pk_add_f32 v[46:47], v[46:47], v[52:53]
	s_nop 0
	v_mul_f32_e32 v52, 0xbfb8aa3b, v46
	v_mul_f32_e32 v53, 0xbfb8aa3b, v47
	v_exp_f32_e32 v52, v52
	v_exp_f32_e32 v53, v53
	v_add_f32_e32 v52, 1.0, v52
	v_add_f32_e32 v53, 1.0, v53
	v_rcp_f32_e32 v52, v52
	v_rcp_f32_e32 v53, v53
	s_nop 0
	v_pk_mul_f32 v[76:77], v[46:47], v[52:53]
	v_lshlrev_b32_e32 v52, 16, v48
	v_and_b32_e32 v53, 0xffff0000, v48
	v_pk_mul_f32 v[46:47], v[14:15], v[58:59]
	v_cvt_pk_bf16_f32 v73, v76, v77
	v_pk_fma_f32 v[46:47], v[10:11], v[68:69], v[46:47]
	v_pk_mul_f32 v[68:69], v[22:23], v[52:53]
	v_ashrrev_i32_e32 v76, 5, v104
	v_pk_fma_f32 v[68:69], v[18:19], v[4:5], v[68:69]
	v_ashrrev_i32_e32 v77, 31, v76
	v_pk_add_f32 v[46:47], v[46:47], v[68:69]
	s_nop 0
	v_mul_f32_e32 v48, 0xbfb8aa3b, v46
	v_exp_f32_e32 v48, v48
	s_nop 0
	v_add_f32_e32 v48, 1.0, v48
	v_rcp_f32_e32 v68, v48
	v_mul_f32_e32 v48, 0xbfb8aa3b, v47
	v_exp_f32_e32 v48, v48
	s_nop 0
	v_add_f32_e32 v48, 1.0, v48
	v_rcp_f32_e32 v69, v48
	s_nop 0
	v_pk_mul_f32 v[68:69], v[46:47], v[68:69]
	v_lshlrev_b32_e32 v46, 16, v49
	v_and_b32_e32 v47, 0xffff0000, v49
	v_pk_mul_f32 v[48:49], v[16:17], v[56:57]
	v_cvt_pk_bf16_f32 v74, v68, v69
	v_pk_fma_f32 v[48:49], v[12:13], v[64:65], v[48:49]
	v_pk_mul_f32 v[64:65], v[24:25], v[46:47]
	v_lshlrev_b32_e32 v68, 16, v40
	v_pk_fma_f32 v[64:65], v[20:21], v[2:3], v[64:65]
	v_and_b32_e32 v69, 0xffff0000, v40
	v_pk_add_f32 v[48:49], v[48:49], v[64:65]
	s_nop 0
	v_mul_f32_e32 v64, 0xbfb8aa3b, v48
	v_mul_f32_e32 v65, 0xbfb8aa3b, v49
	v_exp_f32_e32 v64, v64
	v_exp_f32_e32 v65, v65
	v_add_f32_e32 v64, 1.0, v64
	v_add_f32_e32 v65, 1.0, v65
	v_rcp_f32_e32 v64, v64
	v_rcp_f32_e32 v65, v65
	s_nop 0
	v_pk_mul_f32 v[48:49], v[48:49], v[64:65]
	s_nop 0
	v_cvt_pk_bf16_f32 v75, v48, v49
	v_lshlrev_b32_e32 v48, 16, v38
	v_and_b32_e32 v49, 0xffff0000, v38
	v_pk_mul_f32 v[64:65], v[30:31], v[54:55]
	ds_write_b128 v94, v[72:75] offset:2720
	v_pk_fma_f32 v[62:63], v[26:27], v[62:63], v[64:65]
	v_pk_mul_f32 v[64:65], v[42:43], v[48:49]
	v_lshlrev_b32_e32 v72, 16, v41
	v_pk_fma_f32 v[64:65], v[34:35], v[70:71], v[64:65]
	v_and_b32_e32 v73, 0xffff0000, v41
	v_pk_add_f32 v[62:63], v[62:63], v[64:65]
	v_pk_mul_f32 v[30:31], v[30:31], v[70:71]
	v_mul_f32_e32 v38, 0xbfb8aa3b, v62
	v_exp_f32_e32 v38, v38
	v_pk_fma_f32 v[26:27], v[26:27], v[54:55], v[30:31]
	v_add_f32_e32 v38, 1.0, v38
	v_rcp_f32_e32 v64, v38
	v_mul_f32_e32 v38, 0xbfb8aa3b, v63
	v_exp_f32_e32 v38, v38
	s_nop 0
	v_add_f32_e32 v38, 1.0, v38
	v_rcp_f32_e32 v65, v38
	s_nop 0
	v_pk_mul_f32 v[62:63], v[62:63], v[64:65]
	v_lshlrev_b32_e32 v64, 16, v39
	v_and_b32_e32 v65, 0xffff0000, v39
	v_pk_mul_f32 v[38:39], v[32:33], v[50:51]
	s_nop 0
	v_pk_fma_f32 v[38:39], v[28:29], v[60:61], v[38:39]
	v_pk_mul_f32 v[60:61], v[44:45], v[64:65]
	s_nop 0
	v_pk_fma_f32 v[60:61], v[36:37], v[66:67], v[60:61]
	s_nop 0
	v_pk_add_f32 v[38:39], v[38:39], v[60:61]
	s_nop 0
	v_mul_f32_e32 v60, 0xbfb8aa3b, v38
	v_mul_f32_e32 v61, 0xbfb8aa3b, v39
	v_exp_f32_e32 v60, v60
	v_exp_f32_e32 v61, v61
	v_add_f32_e32 v60, 1.0, v60
	v_add_f32_e32 v61, 1.0, v61
	v_rcp_f32_e32 v60, v60
	v_rcp_f32_e32 v61, v61
	s_nop 0
	v_pk_mul_f32 v[60:61], v[38:39], v[60:61]
	v_pk_mul_f32 v[38:39], v[14:15], v[4:5]
	v_pk_mul_f32 v[14:15], v[14:15], v[52:53]
	v_pk_fma_f32 v[38:39], v[10:11], v[58:59], v[38:39]
	v_pk_mul_f32 v[58:59], v[22:23], v[68:69]
	v_pk_fma_f32 v[4:5], v[10:11], v[4:5], v[14:15]
	v_pk_fma_f32 v[58:59], v[18:19], v[52:53], v[58:59]
	s_nop 0
	v_pk_add_f32 v[38:39], v[38:39], v[58:59]
	s_nop 0
	v_mul_f32_e32 v40, 0xbfb8aa3b, v38
	v_exp_f32_e32 v40, v40
	s_nop 0
	v_add_f32_e32 v40, 1.0, v40
	v_rcp_f32_e32 v58, v40
	v_mul_f32_e32 v40, 0xbfb8aa3b, v39
	v_exp_f32_e32 v40, v40
	s_nop 0
	v_add_f32_e32 v40, 1.0, v40
	v_rcp_f32_e32 v59, v40
	v_pk_mul_f32 v[40:41], v[24:25], v[72:73]
	v_pk_mul_f32 v[58:59], v[38:39], v[58:59]
	v_pk_mul_f32 v[38:39], v[16:17], v[2:3]
	v_pk_fma_f32 v[40:41], v[20:21], v[46:47], v[40:41]
	v_pk_fma_f32 v[38:39], v[12:13], v[56:57], v[38:39]
	s_nop 0
	v_pk_add_f32 v[38:39], v[38:39], v[40:41]
	s_nop 0
	v_mul_f32_e32 v40, 0xbfb8aa3b, v38
	v_mul_f32_e32 v41, 0xbfb8aa3b, v39
	v_exp_f32_e32 v40, v40
	v_exp_f32_e32 v41, v41
	v_add_f32_e32 v40, 1.0, v40
	v_add_f32_e32 v41, 1.0, v41
	v_rcp_f32_e32 v40, v40
	v_rcp_f32_e32 v41, v41
	s_nop 0
	v_pk_mul_f32 v[56:57], v[38:39], v[40:41]
	v_cvt_pk_bf16_f32 v38, v62, v63
; __device__ __forceinline__ float fsigmoid(float x) { return __builtin_amdgcn_rcpf(1.0f + __expf(-x)); }
; #define LAS __attribute__((address_space(3)))
; __device__ __forceinline__ void load_conv(LAS char* dst, const bf16_t* src, int pos0, const float* cw  , const LAS float* rowscale, float cscale, int tid) {
;     ...
;     for (int r = 0; r < 8; ++r) {
;         float x[8]; unpack8(rw[3 + r], x);
;         const float sc = sc8[r];
;         float o[8];
; #pragma unroll
;         for (int e = 0; e < 8; ++e) { const float cv = (w[0][e] * u[0][e] + w[1][e] * u[1][e]) + (w[2][e] * u[2][e] + w[3][e] * x[e]); o[e] = cv * fsigmoid(cv) * sc;
;             u[0][e] = u[1][e]; u[1][e] = u[2][e]; u[2][e] = x[e]; }
;         *(LAS u32x4*)(dst + (r0 + r) * PIT + cg * 16) = pack8(o);
; __device__ __forceinline__ void m3_item(LAS char* lds, bf16_t* proj, const float* gif, const bf16_t* Cst, const float* nst, const float* mprev, const float* convw, int bhl, int c) {
;     ...
;     __syncthreads();
;     const int j0 = 16 * wid, jj = j0 + fr;
;     bf16x8 pf[4]; float den, inter, mt;
;     u32x4 pre[8];
;     load_plain_issue(pre, Cst + (size_t)item * 65536, 256, tid);
;     {
;         f32x4 S[8];
; #pragma unroll
;         for (int sb = 0; sb < 8; ++sb) S[sb] = (f32x4){0.f, 0.f, 0.f, 0.f};
	v_cvt_pk_bf16_f32 v39, v60, v61
	v_cvt_pk_bf16_f32 v40, v58, v59
	v_cvt_pk_bf16_f32 v41, v56, v57
	ds_write_b128 v94, v[38:41] offset:3264
	v_lshlrev_b32_e32 v38, 16, v6
	v_and_b32_e32 v39, 0xffff0000, v6
	v_pk_mul_f32 v[30:31], v[42:43], v[38:39]
	s_nop 0
	v_pk_fma_f32 v[30:31], v[34:35], v[48:49], v[30:31]
	s_nop 0
	v_pk_add_f32 v[26:27], v[26:27], v[30:31]
	s_nop 0
	v_mul_f32_e32 v6, 0xbfb8aa3b, v26
	v_exp_f32_e32 v6, v6
	s_nop 0
	v_add_f32_e32 v6, 1.0, v6
	v_rcp_f32_e32 v30, v6
	v_mul_f32_e32 v6, 0xbfb8aa3b, v27
	v_exp_f32_e32 v6, v6
	s_nop 0
	v_add_f32_e32 v6, 1.0, v6
	v_rcp_f32_e32 v31, v6
	v_lshlrev_b32_e32 v6, 16, v7
	v_and_b32_e32 v7, 0xffff0000, v7
	v_pk_mul_f32 v[6:7], v[44:45], v[6:7]
	v_pk_mul_f32 v[26:27], v[26:27], v[30:31]
	v_pk_mul_f32 v[30:31], v[32:33], v[66:67]
	v_pk_fma_f32 v[6:7], v[36:37], v[64:65], v[6:7]
	v_pk_fma_f32 v[28:29], v[28:29], v[50:51], v[30:31]
	v_mov_b32_e32 v37, s1
	v_pk_add_f32 v[6:7], v[28:29], v[6:7]
	v_and_b32_e32 v36, 48, v104
	v_mul_f32_e32 v28, 0xbfb8aa3b, v6
	v_mul_f32_e32 v29, 0xbfb8aa3b, v7
	v_exp_f32_e32 v28, v28
	v_exp_f32_e32 v29, v29
	v_mad_u32_u24 v75, v105, s13, v37
	v_mov_b32_e32 v64, 0
	v_add_f32_e32 v28, 1.0, v28
	v_add_f32_e32 v29, 1.0, v29
	v_rcp_f32_e32 v28, v28
	v_rcp_f32_e32 v29, v29
	v_mov_b32_e32 v65, v64
	v_mov_b32_e32 v66, v64
	v_mov_b32_e32 v67, v64
	v_pk_mul_f32 v[6:7], v[6:7], v[28:29]
	v_lshlrev_b32_e32 v28, 16, v8
	v_and_b32_e32 v29, 0xffff0000, v8
	v_pk_mul_f32 v[10:11], v[22:23], v[28:29]
	v_mov_b32_e32 v60, v64
	v_pk_fma_f32 v[10:11], v[18:19], v[68:69], v[10:11]
	v_add3_u32 v68, v75, v36, 0
	v_pk_add_f32 v[4:5], v[4:5], v[10:11]
	v_mov_b32_e32 v61, v64
	v_mul_f32_e32 v8, 0xbfb8aa3b, v4
	v_exp_f32_e32 v8, v8
	v_mov_b32_e32 v62, v64
	v_mov_b32_e32 v63, v64
	v_mov_b32_e32 v56, v64
	v_add_f32_e32 v8, 1.0, v8
	v_rcp_f32_e32 v10, v8
	v_mul_f32_e32 v8, 0xbfb8aa3b, v5
	v_exp_f32_e32 v8, v8
	v_mov_b32_e32 v57, v64
	v_mov_b32_e32 v58, v64
	v_mov_b32_e32 v59, v64
	v_add_f32_e32 v8, 1.0, v8
	v_rcp_f32_e32 v11, v8
	v_lshlrev_b32_e32 v8, 16, v9
	v_and_b32_e32 v9, 0xffff0000, v9
	v_pk_mul_f32 v[8:9], v[24:25], v[8:9]
	v_pk_mul_f32 v[4:5], v[4:5], v[10:11]
	v_pk_mul_f32 v[10:11], v[16:17], v[46:47]
	v_pk_fma_f32 v[8:9], v[20:21], v[72:73], v[8:9]
	v_pk_fma_f32 v[2:3], v[12:13], v[2:3], v[10:11]
	v_cvt_pk_bf16_f32 v4, v4, v5
	v_pk_add_f32 v[2:3], v[2:3], v[8:9]
	v_mov_b32_e32 v52, v64
	v_mul_f32_e32 v8, 0xbfb8aa3b, v2
	v_mul_f32_e32 v9, 0xbfb8aa3b, v3
	v_exp_f32_e32 v8, v8
	v_exp_f32_e32 v9, v9
	v_mov_b32_e32 v53, v64
	v_mov_b32_e32 v54, v64
	v_add_f32_e32 v8, 1.0, v8
	v_add_f32_e32 v9, 1.0, v9
	v_rcp_f32_e32 v8, v8
	v_rcp_f32_e32 v9, v9
	v_mov_b32_e32 v55, v64
	v_mov_b32_e32 v48, v64
	v_mov_b32_e32 v49, v64
	v_pk_mul_f32 v[8:9], v[2:3], v[8:9]
	v_cvt_pk_bf16_f32 v2, v26, v27
	v_cvt_pk_bf16_f32 v3, v6, v7
	v_cvt_pk_bf16_f32 v5, v8, v9
	ds_write_b128 v0, v[2:5]
	v_lshlrev_b32_e32 v0, 3, v104
	v_and_b32_e32 v74, 0xf8, v0
	v_lshlrev_b32_e32 v0, 1, v74
	v_lshl_add_u64 v[32:33], s[60:61], 0, v[0:1]
	v_add_u32_e32 v0, 0x200, v104
	v_ashrrev_i32_e32 v80, 5, v0
	v_add_u32_e32 v0, 0x400, v104
	v_ashrrev_i32_e32 v84, 5, v0
	v_add_u32_e32 v0, 0x600, v104
	v_ashrrev_i32_e32 v86, 5, v0
	v_add_u32_e32 v0, 0x800, v104
	v_ashrrev_i32_e32 v90, 5, v0
	v_add_u32_e32 v0, 0xa00, v104
	v_ashrrev_i32_e32 v94, 5, v0
	v_add_u32_e32 v0, 0xc00, v104
	v_ashrrev_i32_e32 v81, 31, v80
	v_ashrrev_i32_e32 v98, 5, v0
	v_add_u32_e32 v0, 0xe00, v104
	v_lshlrev_b64 v[4:5], 9, v[76:77]
	v_lshlrev_b64 v[8:9], 9, v[80:81]
	v_ashrrev_i32_e32 v102, 5, v0
	v_lshl_add_u64 v[4:5], v[32:33], 0, v[4:5]
	v_lshl_add_u64 v[8:9], v[32:33], 0, v[8:9]
	v_ashrrev_i32_e32 v85, 31, v84
	v_ashrrev_i32_e32 v87, 31, v86
	v_ashrrev_i32_e32 v91, 31, v90
	v_ashrrev_i32_e32 v95, 31, v94
	v_ashrrev_i32_e32 v99, 31, v98
	v_ashrrev_i32_e32 v103, 31, v102
	s_waitcnt lgkmcnt(0)
	s_barrier
	global_load_dwordx4 v[4:7], v[4:5], off
	v_lshlrev_b64 v[16:17], 9, v[86:87]
	global_load_dwordx4 v[12:15], v[8:9], off
	v_lshlrev_b64 v[8:9], 9, v[84:85]
	v_lshlrev_b64 v[20:21], 9, v[90:91]
	v_lshlrev_b64 v[24:25], 9, v[94:95]
	v_lshlrev_b64 v[28:29], 9, v[98:99]
	v_lshlrev_b64 v[34:35], 9, v[102:103]
	v_lshl_add_u64 v[8:9], v[32:33], 0, v[8:9]
	v_lshl_add_u64 v[16:17], v[32:33], 0, v[16:17]
	v_lshl_add_u64 v[20:21], v[32:33], 0, v[20:21]
	v_lshl_add_u64 v[24:25], v[32:33], 0, v[24:25]
	v_lshl_add_u64 v[28:29], v[32:33], 0, v[28:29]
	v_lshl_add_u64 v[32:33], v[32:33], 0, v[34:35]
	global_load_dwordx4 v[8:11], v[8:9], off
	v_mul_u32_u24_e32 v0, 0x220, v105
	global_load_dwordx4 v[16:19], v[16:17], off
	v_lshlrev_b64 v[2:3], 8, v[76:77]
	global_load_dwordx4 v[20:23], v[20:21], off
	v_lshlrev_b64 v[72:73], 8, v[80:81]
	global_load_dwordx4 v[24:27], v[24:25], off
	v_lshlrev_b64 v[78:79], 8, v[84:85]
	global_load_dwordx4 v[28:31], v[28:29], off
	v_lshlrev_b64 v[82:83], 8, v[86:87]
	global_load_dwordx4 v[32:35], v[32:33], off
	v_lshlrev_b64 v[88:89], 8, v[90:91]
	v_lshlrev_b64 v[92:93], 8, v[94:95]
	v_lshlrev_b64 v[96:97], 8, v[98:99]
	v_lshlrev_b64 v[100:101], 8, v[102:103]
	v_add3_u32 v0, v0, v36, 0
	v_mov_b32_e32 v50, v64
	v_mov_b32_e32 v51, v64
	v_mov_b32_e32 v44, v64
	v_mov_b32_e32 v45, v64
	v_mov_b32_e32 v46, v64
	v_mov_b32_e32 v47, v64
	v_mov_b32_e32 v40, v64
	v_mov_b32_e32 v41, v64
	v_mov_b32_e32 v42, v64
	v_mov_b32_e32 v43, v64
	v_mov_b32_e32 v36, v64
	v_mov_b32_e32 v37, v64
	v_mov_b32_e32 v38, v64
	v_mov_b32_e32 v39, v64

; __device__ __forceinline__ f32x4 mfma16(bf16x8 a, bf16x8 b, f32x4 c) { return __builtin_amdgcn_mfma_f32_16x16x32_bf16(a, b, c, 0, 0, 0); }
; __device__ __forceinline__ void m3_item(LAS char* lds, bf16_t* proj, const float* gif, const bf16_t* Cst, const float* nst, const float* mprev, const float* convw, int bhl, int c) {
;     ...
;     for (int half = 0; half < 2; ++half) {
;         __syncthreads();
;         load_plain_commit(Y, pre, tid);
;         if (half == 0) load_plain_issue(pre, Cst + (size_t)item * 65536 + 32768, 256, tid);
;         else load_plain_issue(pre, proj + SEC(C_MV) + (size_t)t0 * PP + h * 256, PP, tid);
;         __syncthreads();
; #pragma unroll 1
;         for (int t = 0; t < 4; ++t) { const bf16x8 qb = rowfrag_perm(X, PIT, j0, half * 128 + 32 * t, lane);
; #pragma unroll
;             for (int hb = 0; hb < 2; ++hb) {
;                 bf16x8 cf[8];
; #pragma unroll
;                 for (int nb = 0; nb < 8; ++nb) cf[nb] = trfrag(Y, PIT, 32 * t, 16 * (8 * hb + nb), lane);
;                 __builtin_amdgcn_sched_barrier(0);
; #pragma unroll
;                 for (int nb = 0; nb < 8; ++nb) acc[8 * hb + nb] = mfma16(cf[nb], qb, acc[8 * hb + nb]); } }
;     }
; #pragma unroll
;     for (int nb = 0; nb < 16; ++nb) acc[nb] = acc[nb] * inter;
.LBB0_196:
	v_add_u32_e32 v3, 0, v0
	ds_read2_b64 v[96:99], v3 offset1:4
	v_add_u32_e32 v3, 0, v2
	v_add_u32_e32 v191, 0x11000, v3
	v_add_u32_e32 v192, 0x13200, v3
	v_add_u32_e32 v193, 0x11020, v3
	v_add_u32_e32 v205, 0x13220, v3
	ds_read_b64_tr_b16 v[206:207], v191
	ds_read_b64_tr_b16 v[208:209], v192
	ds_read_b64_tr_b16 v[210:211], v193
	ds_read_b64_tr_b16 v[212:213], v205
	v_add_u32_e32 v191, 0x11040, v3
	v_add_u32_e32 v192, 0x13240, v3
	v_add_u32_e32 v193, 0x11060, v3
	v_add_u32_e32 v205, 0x13260, v3
	ds_read_b64_tr_b16 v[214:215], v191
	ds_read_b64_tr_b16 v[216:217], v192
	ds_read_b64_tr_b16 v[218:219], v193
	ds_read_b64_tr_b16 v[220:221], v205
	v_add_u32_e32 v191, 0x11080, v3
	v_add_u32_e32 v192, 0x13280, v3
	v_add_u32_e32 v193, 0x110a0, v3
	v_add_u32_e32 v205, 0x132a0, v3
	ds_read_b64_tr_b16 v[222:223], v191
	ds_read_b64_tr_b16 v[224:225], v192
	ds_read_b64_tr_b16 v[226:227], v193
	ds_read_b64_tr_b16 v[228:229], v205
	v_add_u32_e32 v191, 0x110c0, v3
	v_add_u32_e32 v192, 0x132c0, v3
	v_add_u32_e32 v193, 0x110e0, v3
	v_add_u32_e32 v205, 0x132e0, v3
	ds_read_b64_tr_b16 v[238:239], v191
	ds_read_b64_tr_b16 v[240:241], v192
	ds_read_b64_tr_b16 v[244:245], v193
	ds_read_b64_tr_b16 v[246:247], v205
	v_add_u32_e32 v191, 0x11100, v3
	s_waitcnt lgkmcnt(14)
	v_mfma_f32_16x16x32_bf16 v[92:95], v[206:209], v[96:99], v[92:95]
	ds_read_b64_tr_b16 v[206:207], v191
	v_add_u32_e32 v191, 0x13300, v3
	ds_read_b64_tr_b16 v[208:209], v191
	v_add_u32_e32 v191, 0x11120, v3
	s_waitcnt lgkmcnt(14)
	v_mfma_f32_16x16x32_bf16 v[88:91], v[210:213], v[96:99], v[88:91]
	ds_read_b64_tr_b16 v[210:211], v191
	v_add_u32_e32 v191, 0x13320, v3
	ds_read_b64_tr_b16 v[212:213], v191
	v_add_u32_e32 v191, 0x11140, v3
	s_waitcnt lgkmcnt(14)
	v_mfma_f32_16x16x32_bf16 v[84:87], v[214:217], v[96:99], v[84:87]
	ds_read_b64_tr_b16 v[214:215], v191
	v_add_u32_e32 v191, 0x13340, v3
	ds_read_b64_tr_b16 v[216:217], v191
	v_add_u32_e32 v191, 0x11160, v3
	s_waitcnt lgkmcnt(14)
	v_mfma_f32_16x16x32_bf16 v[80:83], v[218:221], v[96:99], v[80:83]
	ds_read_b64_tr_b16 v[218:219], v191
	v_add_u32_e32 v191, 0x13360, v3
	ds_read_b64_tr_b16 v[220:221], v191
	v_add_u32_e32 v191, 0x11180, v3
	s_waitcnt lgkmcnt(14)
	v_mfma_f32_16x16x32_bf16 v[76:79], v[222:225], v[96:99], v[76:79]
	ds_read_b64_tr_b16 v[222:223], v191
	v_add_u32_e32 v191, 0x13380, v3
	ds_read_b64_tr_b16 v[224:225], v191
	v_add_u32_e32 v191, 0x111a0, v3
	s_waitcnt lgkmcnt(14)
	v_mfma_f32_16x16x32_bf16 v[72:75], v[226:229], v[96:99], v[72:75]
	ds_read_b64_tr_b16 v[226:227], v191
	v_add_u32_e32 v191, 0x133a0, v3
	ds_read_b64_tr_b16 v[228:229], v191
	v_add_u32_e32 v191, 0x111c0, v3
	s_waitcnt lgkmcnt(14)
	v_mfma_f32_16x16x32_bf16 v[68:71], v[238:241], v[96:99], v[68:71]
	ds_read_b64_tr_b16 v[238:239], v191
	v_add_u32_e32 v191, 0x133c0, v3
	ds_read_b64_tr_b16 v[240:241], v191
	v_add_u32_e32 v191, 0x111e0, v3
	v_add_u32_e32 v3, 0x133e0, v3
	s_waitcnt lgkmcnt(14)
	v_mfma_f32_16x16x32_bf16 v[64:67], v[244:247], v[96:99], v[64:67]
	ds_read_b64_tr_b16 v[244:245], v191
	ds_read_b64_tr_b16 v[246:247], v3
	s_waitcnt lgkmcnt(14)
	v_mfma_f32_16x16x32_bf16 v[100:103], v[206:209], v[96:99], v[100:103]
	s_add_i32 s4, s4, -1
	v_add_u32_e32 v2, 0x4400, v2
	v_add_u32_e32 v0, 64, v0
	s_waitcnt lgkmcnt(12)
	v_mfma_f32_16x16x32_bf16 v[60:63], v[210:213], v[96:99], v[60:63]
	s_cmp_eq_u32 s4, 0
	s_waitcnt lgkmcnt(10)
	v_mfma_f32_16x16x32_bf16 v[56:59], v[214:217], v[96:99], v[56:59]
	s_waitcnt lgkmcnt(8)
	v_mfma_f32_16x16x32_bf16 v[52:55], v[218:221], v[96:99], v[52:55]
	s_waitcnt lgkmcnt(6)
	v_mfma_f32_16x16x32_bf16 v[48:51], v[222:225], v[96:99], v[48:51]
	s_waitcnt lgkmcnt(4)
	v_mfma_f32_16x16x32_bf16 v[44:47], v[226:229], v[96:99], v[44:47]
	s_waitcnt lgkmcnt(2)
	v_mfma_f32_16x16x32_bf16 v[40:43], v[238:241], v[96:99], v[40:43]
	s_waitcnt lgkmcnt(0)
	v_mfma_f32_16x16x32_bf16 v[36:39], v[244:247], v[96:99], v[36:39]
	s_cbranch_scc0 .LBB0_196
	s_movk_i32 s87, 0x80
	s_mov_b64 s[4:5], 0
	s_and_b64 vcc, exec, s[0:1]
	s_cbranch_vccz .LBB0_191
	v_sub_f32_e32 v0, v178, v144
	v_mul_f32_e32 v0, 0x3fb8aa3b, v0
	v_exp_f32_e32 v0, v0
	s_barrier
; __device__ __forceinline__ f32x4 mfma16(bf16x8 a, bf16x8 b, f32x4 c) { return __builtin_amdgcn_mfma_f32_16x16x32_bf16(a, b, c, 0, 0, 0); }
; __device__ __forceinline__ void m3_item(LAS char* lds, bf16_t* proj, const float* gif, const bf16_t* Cst, const float* nst, const float* mprev, const float* convw, int bhl, int c) {
;     ...
;     for (int nb = 0; nb < 16; ++nb) acc[nb] = acc[nb] * inter;
;     __syncthreads();
;     load_plain_commit(X, pre, tid);
;     __syncthreads();
; #pragma unroll
;     for (int t = 0; t < 4; ++t) if (2 * t <= wid) {
;         bf16x8 vf[16];
; #pragma unroll
;         for (int nb = 0; nb < 16; ++nb) vf[nb] = trfrag(X, PIT, 32 * t, 16 * nb, lane);
;         __builtin_amdgcn_sched_barrier(0);
; #pragma unroll
;         for (int nb = 0; nb < 16; ++nb) acc[nb] = mfma16(vf[nb], pf[t], acc[nb]); }
;     const float rdn = 1.0f / fmaxf(fabsf(den), __expf(-mt));
;     bf16_t* op = proj + SEC(C_MO) + (size_t)(t0 + jj) * PP + h * 256 + 4 * g;
;     u32x2 sgv[16];
; #pragma unroll
;     for (int nb = 0; nb < 16; ++nb) sgv[nb] = *(const u32x2*)(op + 16 * nb);
	v_pk_mul_f32 v[96:97], v[0:1], v[92:93] op_sel_hi:[0,1]
	v_pk_mul_f32 v[92:93], v[0:1], v[88:89] op_sel_hi:[0,1]
	v_pk_mul_f32 v[88:89], v[0:1], v[84:85] op_sel_hi:[0,1]
	v_pk_mul_f32 v[84:85], v[0:1], v[80:81] op_sel_hi:[0,1]
	v_pk_mul_f32 v[80:81], v[0:1], v[76:77] op_sel_hi:[0,1]
	v_pk_mul_f32 v[76:77], v[0:1], v[72:73] op_sel_hi:[0,1]
	v_pk_mul_f32 v[72:73], v[0:1], v[68:69] op_sel_hi:[0,1]
	v_pk_mul_f32 v[68:69], v[0:1], v[64:65] op_sel_hi:[0,1]
	v_pk_mul_f32 v[64:65], v[0:1], v[100:101] op_sel_hi:[0,1]
	v_add_u32_e32 v100, 0, v188
	v_add_u32_e32 v101, v100, v187
	s_waitcnt vmcnt(7)
	ds_write_b128 v101, v[4:7]
	v_add_u32_e32 v4, v100, v186
	s_waitcnt vmcnt(6)
	ds_write_b128 v4, v[12:15]
	v_add_u32_e32 v4, v100, v185
	s_waitcnt vmcnt(5)
	ds_write_b128 v4, v[8:11]
	v_add_u32_e32 v4, v100, v184
	v_pk_add_f32 v[2:3], v[106:107], v[108:109]
	s_waitcnt vmcnt(4)
	ds_write_b128 v4, v[16:19]
	v_add_u32_e32 v4, v100, v183
	ds_bpermute_b32 v106, v143, v2
	ds_bpermute_b32 v107, v143, v3
	s_waitcnt vmcnt(3)
	ds_write_b128 v4, v[20:23]
	v_add_u32_e32 v4, v100, v182
	s_waitcnt vmcnt(2)
	ds_write_b128 v4, v[24:27]
	v_add_u32_e32 v4, v100, v180
	s_waitcnt vmcnt(1)
	ds_write_b128 v4, v[28:31]
	v_add_u32_e32 v4, v100, v181
	s_waitcnt vmcnt(0)
	v_readlane_b32 s98, v252, 18
	v_readlane_b32 s99, v252, 19
	v_add_u32_e32 v248, s74, v105
	v_ashrrev_i32_e32 v249, 31, v248
	v_lshlrev_b64 v[248:249], 11, v[248:249]
	v_lshl_add_u64 v[248:249], s[98:99], 0, v[248:249]
	v_lshl_add_u64 v[248:249], v[248:249], 0, s[84:85]
	v_lshlrev_b32_e32 v250, 1, v142
	v_mov_b32_e32 v251, 0
	v_lshl_add_u64 v[248:249], v[248:249], 0, v[250:251]
	global_load_dwordx2 v[206:207], v[248:249], off
	global_load_dwordx2 v[208:209], v[248:249], off offset:32
	global_load_dwordx2 v[210:211], v[248:249], off offset:64
	global_load_dwordx2 v[212:213], v[248:249], off offset:96
	global_load_dwordx2 v[214:215], v[248:249], off offset:128
	global_load_dwordx2 v[216:217], v[248:249], off offset:160
	global_load_dwordx2 v[218:219], v[248:249], off offset:192
	global_load_dwordx2 v[220:221], v[248:249], off offset:224
	global_load_dwordx2 v[222:223], v[248:249], off offset:256
	global_load_dwordx2 v[224:225], v[248:249], off offset:288
	global_load_dwordx2 v[226:227], v[248:249], off offset:320
	global_load_dwordx2 v[228:229], v[248:249], off offset:352
	global_load_dwordx2 v[238:239], v[248:249], off offset:384
	global_load_dwordx2 v[240:241], v[248:249], off offset:416
	global_load_dwordx2 v[244:245], v[248:249], off offset:448
	global_load_dwordx2 v[246:247], v[248:249], off offset:480
	ds_write_b128 v4, v[32:35]
	v_bfe_u32 v4, v104, 2, 4
	v_add_u32_e32 v5, 0, v179
	v_pk_mul_f32 v[98:99], v[0:1], v[94:95] op_sel_hi:[0,1]
	v_pk_mul_f32 v[94:95], v[0:1], v[90:91] op_sel_hi:[0,1]
	v_pk_mul_f32 v[90:91], v[0:1], v[86:87] op_sel_hi:[0,1]
	v_pk_mul_f32 v[86:87], v[0:1], v[82:83] op_sel_hi:[0,1]
	v_pk_mul_f32 v[82:83], v[0:1], v[78:79] op_sel_hi:[0,1]
	v_pk_mul_f32 v[78:79], v[0:1], v[74:75] op_sel_hi:[0,1]
	v_pk_mul_f32 v[74:75], v[0:1], v[70:71] op_sel_hi:[0,1]
	v_pk_mul_f32 v[70:71], v[0:1], v[66:67] op_sel_hi:[0,1]
	v_pk_mul_f32 v[66:67], v[0:1], v[102:103] op_sel_hi:[0,1]
	v_pk_mul_f32 v[62:63], v[0:1], v[62:63] op_sel_hi:[0,1]
	v_pk_mul_f32 v[60:61], v[0:1], v[60:61] op_sel_hi:[0,1]
	v_pk_mul_f32 v[58:59], v[0:1], v[58:59] op_sel_hi:[0,1]
	v_pk_mul_f32 v[56:57], v[0:1], v[56:57] op_sel_hi:[0,1]
	v_pk_mul_f32 v[54:55], v[0:1], v[54:55] op_sel_hi:[0,1]
	v_pk_mul_f32 v[52:53], v[0:1], v[52:53] op_sel_hi:[0,1]
	v_pk_mul_f32 v[50:51], v[0:1], v[50:51] op_sel_hi:[0,1]
	v_pk_mul_f32 v[48:49], v[0:1], v[48:49] op_sel_hi:[0,1]
	v_pk_mul_f32 v[46:47], v[0:1], v[46:47] op_sel_hi:[0,1]
	v_pk_mul_f32 v[44:45], v[0:1], v[44:45] op_sel_hi:[0,1]
	v_pk_mul_f32 v[42:43], v[0:1], v[42:43] op_sel_hi:[0,1]
	v_pk_mul_f32 v[40:41], v[0:1], v[40:41] op_sel_hi:[0,1]
	v_pk_mul_f32 v[38:39], v[0:1], v[38:39] op_sel_hi:[0,1]
	v_pk_mul_f32 v[36:37], v[0:1], v[36:37] op_sel_hi:[0,1]
	s_cmp_gt_i32 s75, -1
	v_mad_u32_u24 v4, v4, s6, v5
	s_waitcnt lgkmcnt(0)
	s_barrier
	s_cbranch_scc1 .LBB0_202
	s_mov_b32 s87, s97
	s_cmp_lt_i32 s75, 2
	s_movk_i32 s97, 0x2000
	s_cbranch_scc0 .LBB0_203
